# v42 + G1 split epilogue: a unit with a successor stores its ai=0 half from its last load segment and its ai=1 half from the next unit's first load segment (no aligned epilogue stop)
# speedup vs baseline: 1.0075x; 1.0075x over previous
;     __host__ __device__ bool next(int i_, Unit& u) const {
;         const int i = i_ + i0; if (i >= i1) return false;
;         const long L = (long)i * G + c; if (L >= nwg) return false;
;         int wgid = (int)L; { const int q = nwg / NXCD, r = nwg % NXCD, xcd = wgid % NXCD, off = wgid / NXCD; wgid = (xcd < r ? xcd * (q + 1) : r * (q + 1) + (xcd - r) * q) + off; }
;         const int nig = WGM * nN, gid = wgid / nig, fm = gid * WGM, gsz = (nM - fm) < WGM ? (nM - fm) : WGM;
;         u.pm = fm + ((wgid % nig) % gsz); u.pn = (wgid % nig) / gsz; return true;
; template <class Epi, class Sched, bool ALIGN_EPI = false, bool SP2 = false, bool KHOOK = false>
; __device__ __forceinline__ void gemm_phase(PG8_LAS unsigned char* lds, const Gemm g, const Sched& S, const Epi& E, const int tid_in) {
;     ...
;         const bool has_next = S.next(ui + 1, nxt);
;         const char* nA = has_next ? (const char*)g.A + (size_t)nxt.pm * tstep + (size_t)nxt.pn * ksl : cA; const char* nB = has_next ? (const char*)g.Bt + (size_t)nxt.pn * bts + (size_t)nxt.pn * ksl + (gdv ? (size_t)(nxt.pm / gdv) * gst : 0) : cB;
.LBB0_259:
	s_add_i32 s41, s41, 1
	s_add_i32 s11, s41, s20
	s_cmp_ge_u32 s11, s36
	s_mov_b64 s[22:23], 0
	s_cbranch_scc1 .LBB0_262
	s_mul_i32 s15, s11, s66
	s_mul_hi_u32 s17, s11, s94
	s_add_i32 s17, s17, s15
	s_mul_i32 s11, s11, s94
	s_add_u32 s18, s11, s92
	s_addc_u32 s19, s17, s80
	v_cmp_gt_i64_e32 vcc, s[18:19], v[194:195]
	s_cbranch_vccnz .LBB0_262
	s_ashr_i32 s11, s18, 31
	s_lshr_b32 s11, s11, 29
	s_add_i32 s11, s18, s11
	s_ashr_i32 s14, s11, 3
	s_and_b32 s11, s11, -8
	s_sub_i32 s11, s18, s11
	s_cmp_lt_i32 s11, 0
	s_cselect_b32 s15, s4, 0x140
	s_mul_i32 s11, s11, s15
	s_add_i32 s11, s11, s14
	s_mul_hi_i32 s14, s11, 0x66666667
	s_lshr_b32 s15, s14, 31
	s_ashr_i32 s14, s14, 7
	s_add_i32 s14, s14, s15
	s_lshl_b32 s15, s14, 2
	s_sub_i32 s16, 32, s15
	s_min_i32 s16, s16, 4
	s_abs_i32 s17, s16
	v_cvt_f32_u32_e32 v224, s17
	s_sub_i32 s19, 0, s17
	s_mulk_i32 s14, 0x140
	s_sub_i32 s11, s11, s14
	v_rcp_iflag_f32_e32 v224, v224
	s_abs_i32 s14, s11
	s_xor_b32 s18, s11, s16
	s_ashr_i32 s18, s18, 31
	v_mul_f32_e32 v224, 0x4f7ffffe, v224
	v_cvt_u32_f32_e32 v224, v224
	s_nop 0
	v_readfirstlane_b32 s22, v224
	s_mul_i32 s19, s19, s22
	s_mul_hi_u32 s19, s22, s19
	s_add_i32 s22, s22, s19
	s_mul_hi_u32 s19, s14, s22
	s_mul_i32 s22, s19, s17
	s_sub_i32 s14, s14, s22
	s_add_i32 s23, s19, 1
	s_sub_i32 s22, s14, s17
	s_cmp_ge_u32 s14, s17
	s_cselect_b32 s19, s23, s19
	s_cselect_b32 s14, s22, s14
	s_add_i32 s22, s19, 1
	s_cmp_ge_u32 s14, s17
	s_cselect_b32 s14, s22, s19
	s_xor_b32 s14, s14, s18
	s_sub_i32 s14, s14, s18
	s_mul_i32 s16, s14, s16
	s_sub_i32 s11, s11, s16
	s_add_i32 s16, s15, s11
	s_mov_b64 s[22:23], -1

; __device__ __forceinline__ unsigned cvt_pk_bf16(float lo, float hi) { const f32x2_t v = {lo, hi}; const bf16x2_t c = __builtin_convertvector(v, bf16x2_t); return __builtin_bit_cast(unsigned, c); }
; #define PG8_STAGE(bufoff, gbase, voff) do { _Pragma("unroll") for (int _i = 0; _i < 2; ++_i) \
;         __builtin_amdgcn_global_load_lds((const unsigned*)((const char*)(gbase) + (voff)[_i]), (PG8_LAS unsigned*)(lds + (bufoff) + ldsw + _i * 8192), 16, 0, 0); } while (0)
; #define PG8_LDA(dst, b, h) do { _Pragma("unroll") for (int m = 0; m < 4; ++m) _Pragma("unroll") for (int k = 0; k < 2; ++k) dst[m][k] = *(const PG8_LAS bf16x8*)(lds + PG8_SA(b, h) + aoff + m * 2048 + k * 1024); } while (0)
; #define PG8_LDB(dst, b, h) do { _Pragma("unroll") for (int n = 0; n < 2; ++n) _Pragma("unroll") for (int k = 0; k < 2; ++k) dst[n][k] = *(const PG8_LAS bf16x8*)(lds + PG8_SB(b, h) + boff + n * 2048 + k * 1024); } while (0)
; #define PG8_BAR __builtin_amdgcn_s_barrier()
;     __device__ __forceinline__ void operator()(const f32x4 (&acc)[2][2][4][2], const Unit& u, int wr, int wc, int fr, int fq) const {
;     ...
;         for (int ai = 0; ai < 2; ++ai)
; #pragma unroll
;             for (int m = 0; m < 4; ++m) { bf16_t* rowp = O + (size_t)(row0 + ai * HALF + m * 16) * ldc + col0;
; #pragma unroll
;                 for (int bj = 0; bj < 2; ++bj) { const f32x4 v0 = acc[ai][bj][m][0], v1 = acc[ai][bj][m][1];
;                     u32x4 w; w.x = cvt_pk_bf16(v0[0], v0[1]); w.y = cvt_pk_bf16(v0[2], v0[3]); w.z = cvt_pk_bf16(v1[0], v1[1]); w.w = cvt_pk_bf16(v1[2], v1[3]);
;                     *(u32x4*)(rowp + bj * HALF) = w; } }
; template <class Epi, class Sched, bool ALIGN_EPI = false, bool SP2 = false, bool KHOOK = false>
; __device__ __forceinline__ void gemm_phase(PG8_LAS unsigned char* lds, const Gemm g, const Sched& S, const Epi& E, const int tid_in) {
;     ...
;             PG8_LDB(B0, 0, 0); PG8_LDB(B1, 0, 1); PG8_SCHED; PG8_LDA(At, 0, 0); PG8_STAGE(PG8_SA(1, 1), a1 + hstep, voffA);
;             PG8_WAIT_V(8); PG8_WAIT_L(0); PG8_BAR; PG8_MMA(0, 0, At, B0); PG8_MMA(0, 1, At, B1); PG8_BAR; PG8_SCHED;
;             PG8_LDA(At, 0, 1); PG8_STAGE(PG8_SB(0, 0), b2, voffB); PG8_STAGE(PG8_SB(0, 1), b2 + hstep, voffB); PG8_STAGE(PG8_SA(0, 0), a2, voffA);
;             PG8_WAIT_V(8); PG8_WAIT_L(0); PG8_BAR; PG8_MMA(1, 0, At, B0); PG8_MMA(1, 1, At, B1); PG8_BAR; PG8_SCHED;
.Lg1_peel_e1:
	s_add_u32 s45, s48, 0xfff80080
	s_addc_u32 s46, s49, -1
	s_add_i32 s47, 0, 0x10000
	s_cmp_eq_u32 s44, 28
	s_cselect_b32 s57, s11, s46
	s_cselect_b32 s56, s17, s45
	s_cselect_b32 s53, s15, s42
	s_cselect_b32 s52, s18, s19
	s_add_i32 s45, 0, 0x14000
	v_add_u32_e32 v156, s47, v141
	v_add_u32_e32 v172, s45, v141
	ds_read_b128 v[144:147], v156
	ds_read_b128 v[148:151], v156 offset:1024
	ds_read_b128 v[152:155], v156 offset:2048
	ds_read_b128 v[156:159], v156 offset:3072
	ds_read_b128 v[160:163], v172
	ds_read_b128 v[164:167], v172 offset:1024
	ds_read_b128 v[168:171], v172 offset:2048
	ds_read_b128 v[172:175], v172 offset:3072
	v_lshl_add_u64 v[192:193], s[48:49], 0, v[136:137]
	s_add_i32 m0, s13, 0xc000
	ds_read_b128 v[176:179], v143
	ds_read_b128 v[180:183], v143 offset:1024
	ds_read_b128 v[184:187], v143 offset:2048
	ds_read_b128 v[188:191], v143 offset:3072
	ds_read_b128 v[198:201], v143 offset:4096
	ds_read_b128 v[202:205], v143 offset:5120
	ds_read_b128 v[206:209], v143 offset:6144
	ds_read_b128 v[210:213], v143 offset:7168
	global_load_lds_dwordx4 v[192:193], off
	v_lshl_add_u64 v[192:193], s[48:49], 0, v[138:139]
	s_add_i32 m0, s13, 0xe000
	s_nop 0
	global_load_lds_dwordx4 v[192:193], off
	v_lshl_add_u32 v246, s68, 8, v140
	v_add_u32_e32 v246, 0x80, v246
	v_lshl_or_b32 v222, s69, 8, v142
	v_lshlrev_b32_e32 v222, 1, v222
	v_mov_b32_e32 v223, 0
	v_mad_u64_u32 v[248:249], s[70:71], v246, s67, v[222:223]
	s_mov_b32 s72, 0xa2000
	s_mov_b32 s73, 0
	v_lshl_add_u64 v[248:249], v[248:249], 0, s[76:77]
	v_cvt_pk_bf16_f32 v62, v62, v63
	v_cvt_pk_bf16_f32 v63, v64, v65
	v_cvt_pk_bf16_f32 v64, v58, v59
	v_cvt_pk_bf16_f32 v65, v60, v61
	global_store_dwordx4 v[248:249], v[62:65], off
	v_cvt_pk_bf16_f32 v46, v46, v47
	v_cvt_pk_bf16_f32 v47, v48, v49
	v_cvt_pk_bf16_f32 v48, v42, v43
	v_cvt_pk_bf16_f32 v49, v44, v45
	global_store_dwordx4 v[248:249], v[46:49], off offset:256
	v_lshl_add_u64 v[248:249], v[248:249], 0, s[72:73]
	v_cvt_pk_bf16_f32 v54, v54, v55
	v_cvt_pk_bf16_f32 v55, v56, v57
	v_cvt_pk_bf16_f32 v56, v50, v51
	v_cvt_pk_bf16_f32 v57, v52, v53
	global_store_dwordx4 v[248:249], v[54:57], off
	v_cvt_pk_bf16_f32 v28, v28, v29
	v_cvt_pk_bf16_f32 v29, v30, v31
	v_cvt_pk_bf16_f32 v30, v24, v25
	v_cvt_pk_bf16_f32 v31, v26, v27
	global_store_dwordx4 v[248:249], v[28:31], off offset:256
	v_lshl_add_u64 v[248:249], v[248:249], 0, s[72:73]
	v_cvt_pk_bf16_f32 v38, v38, v39
	v_cvt_pk_bf16_f32 v39, v40, v41
	v_cvt_pk_bf16_f32 v40, v34, v35
	v_cvt_pk_bf16_f32 v41, v36, v37
	global_store_dwordx4 v[248:249], v[38:41], off
	v_cvt_pk_bf16_f32 v12, v12, v13
	v_cvt_pk_bf16_f32 v13, v14, v15
	v_cvt_pk_bf16_f32 v14, v8, v9
	v_cvt_pk_bf16_f32 v15, v10, v11
	global_store_dwordx4 v[248:249], v[12:15], off offset:256
	v_lshl_add_u64 v[248:249], v[248:249], 0, s[72:73]
	v_cvt_pk_bf16_f32 v20, v20, v21
	v_cvt_pk_bf16_f32 v21, v22, v23
	v_cvt_pk_bf16_f32 v22, v16, v17
	v_cvt_pk_bf16_f32 v23, v18, v19
	global_store_dwordx4 v[248:249], v[20:23], off
	v_cvt_pk_bf16_f32 v4, v4, v5
	v_cvt_pk_bf16_f32 v5, v6, v7
	v_cvt_pk_bf16_f32 v6, v0, v1
	v_cvt_pk_bf16_f32 v7, v2, v3
	global_store_dwordx4 v[248:249], v[4:7], off offset:256
	s_waitcnt vmcnt(24)
	s_waitcnt lgkmcnt(0)
	s_barrier
	s_setprio 1
	s_waitcnt lgkmcnt(0)
	v_mfma_f32_16x16x32_bf16 v[126:129], v[144:147], v[176:179], 0
	v_mfma_f32_16x16x32_bf16 v[122:125], v[152:155], v[176:179], 0
	v_mfma_f32_16x16x32_bf16 v[118:121], v[144:147], v[184:187], 0
	v_mfma_f32_16x16x32_bf16 v[114:117], v[152:155], v[184:187], 0
	v_mfma_f32_16x16x32_bf16 v[102:105], v[144:147], v[198:201], 0
	v_mfma_f32_16x16x32_bf16 v[98:101], v[152:155], v[198:201], 0
	v_mfma_f32_16x16x32_bf16 v[86:89], v[144:147], v[206:209], 0
	v_mfma_f32_16x16x32_bf16 v[82:85], v[152:155], v[206:209], 0
	v_mfma_f32_16x16x32_bf16 v[126:129], v[148:151], v[180:183], v[126:129]
	v_mfma_f32_16x16x32_bf16 v[122:125], v[156:159], v[180:183], v[122:125]
	v_mfma_f32_16x16x32_bf16 v[118:121], v[148:151], v[188:191], v[118:121]
	v_mfma_f32_16x16x32_bf16 v[114:117], v[156:159], v[188:191], v[114:117]
	v_mfma_f32_16x16x32_bf16 v[102:105], v[148:151], v[202:205], v[102:105]
	v_mfma_f32_16x16x32_bf16 v[98:101], v[156:159], v[202:205], v[98:101]
	v_mfma_f32_16x16x32_bf16 v[86:89], v[148:151], v[210:213], v[86:89]
	v_mfma_f32_16x16x32_bf16 v[82:85], v[156:159], v[210:213], v[82:85]
	s_setprio 0
	s_setprio 1
	v_mfma_f32_16x16x32_bf16 v[110:113], v[160:163], v[176:179], 0
	v_mfma_f32_16x16x32_bf16 v[106:109], v[168:171], v[176:179], 0
	v_mfma_f32_16x16x32_bf16 v[94:97], v[160:163], v[184:187], 0
	v_mfma_f32_16x16x32_bf16 v[90:93], v[168:171], v[184:187], 0
	v_mfma_f32_16x16x32_bf16 v[78:81], v[160:163], v[198:201], 0
	v_mfma_f32_16x16x32_bf16 v[74:77], v[168:171], v[198:201], 0
	v_mfma_f32_16x16x32_bf16 v[70:73], v[160:163], v[206:209], 0
	v_mfma_f32_16x16x32_bf16 v[66:69], v[168:171], v[206:209], 0
	v_mfma_f32_16x16x32_bf16 v[110:113], v[164:167], v[180:183], v[110:113]
	v_mfma_f32_16x16x32_bf16 v[106:109], v[172:175], v[180:183], v[106:109]
	v_mfma_f32_16x16x32_bf16 v[94:97], v[164:167], v[188:191], v[94:97]
	v_mfma_f32_16x16x32_bf16 v[90:93], v[172:175], v[188:191], v[90:93]
	v_mfma_f32_16x16x32_bf16 v[78:81], v[164:167], v[202:205], v[78:81]
	v_mfma_f32_16x16x32_bf16 v[74:77], v[172:175], v[202:205], v[74:77]
	v_mfma_f32_16x16x32_bf16 v[70:73], v[164:167], v[210:213], v[70:73]
	v_mfma_f32_16x16x32_bf16 v[66:69], v[172:175], v[210:213], v[66:69]
	s_setprio 0
	s_barrier
; #define PG8_STAGE(bufoff, gbase, voff) do { _Pragma("unroll") for (int _i = 0; _i < 2; ++_i) \
;         __builtin_amdgcn_global_load_lds((const unsigned*)((const char*)(gbase) + (voff)[_i]), (PG8_LAS unsigned*)(lds + (bufoff) + ldsw + _i * 8192), 16, 0, 0); } while (0)
; #define PG8_LDA(dst, b, h) do { _Pragma("unroll") for (int m = 0; m < 4; ++m) _Pragma("unroll") for (int k = 0; k < 2; ++k) dst[m][k] = *(const PG8_LAS bf16x8*)(lds + PG8_SA(b, h) + aoff + m * 2048 + k * 1024); } while (0)
; #define PG8_LDB(dst, b, h) do { _Pragma("unroll") for (int n = 0; n < 2; ++n) _Pragma("unroll") for (int k = 0; k < 2; ++k) dst[n][k] = *(const PG8_LAS bf16x8*)(lds + PG8_SB(b, h) + boff + n * 2048 + k * 1024); } while (0)
; #define PG8_MMA(ai, bj, At, Bt) do { __builtin_amdgcn_s_setprio(1); _Pragma("unroll") for (int m = 0; m < 4; ++m) _Pragma("unroll") for (int n = 0; n < 2; ++n) _Pragma("unroll") for (int k = 0; k < 2; ++k) \
;         acc[ai][bj][m][n] = __builtin_amdgcn_mfma_f32_16x16x32_bf16(Bt[n][k], At[m][k], acc[ai][bj][m][n], 0, 0, 0); __builtin_amdgcn_s_setprio(0); } while (0)
; #define PG8_WAIT_V(n) asm volatile("s_waitcnt vmcnt(" #n ")" ::: "memory")
; #define PG8_WAIT_L(n) asm volatile("s_waitcnt lgkmcnt(" #n ")" ::: "memory")
; #define PG8_BAR __builtin_amdgcn_s_barrier()
; #define PG8_SCHED __builtin_amdgcn_sched_barrier(0)
; template <class Epi, class Sched, bool ALIGN_EPI = false, bool SP2 = false, bool KHOOK = false>
; __device__ __forceinline__ void gemm_phase(PG8_LAS unsigned char* lds, const Gemm g, const Sched& S, const Epi& E, const int tid_in) {
;     ...
;             PG8_LDA(At, 0, 1); PG8_STAGE(PG8_SB(0, 0), b2, voffB); PG8_STAGE(PG8_SB(0, 1), b2 + hstep, voffB); PG8_STAGE(PG8_SA(0, 0), a2, voffA);
;             PG8_WAIT_V(8); PG8_WAIT_L(0); PG8_BAR; PG8_MMA(1, 0, At, B0); PG8_MMA(1, 1, At, B1); PG8_BAR; PG8_SCHED;
;             PG8_LDB(B0, 1, 0); PG8_LDB(B1, 1, 1); PG8_SCHED; PG8_LDA(At, 1, 0); PG8_STAGE(PG8_SA(0, 1), a2 + hstep, voffA);
;             PG8_WAIT_V(8); PG8_WAIT_L(0); PG8_BAR; PG8_MMA(0, 0, At, B0); PG8_MMA(0, 1, At, B1); PG8_BAR; PG8_SCHED;
	s_add_i32 s46, s47, s37
	v_lshl_add_u64 v[192:193], s[52:53], 0, v[32:33]
	s_mov_b32 m0, s46
	ds_read_b128 v[176:179], v143 offset:16384
	ds_read_b128 v[180:183], v143 offset:17408
	ds_read_b128 v[184:187], v143 offset:18432
	ds_read_b128 v[188:191], v143 offset:19456
	ds_read_b128 v[198:201], v143 offset:20480
	ds_read_b128 v[202:205], v143 offset:21504
	ds_read_b128 v[206:209], v143 offset:22528
	ds_read_b128 v[210:213], v143 offset:23552
	global_load_lds_dwordx4 v[192:193], off
	s_add_i32 m0, s46, 0x2000
	s_add_u32 s46, s52, 0x80000
	v_lshl_add_u64 v[214:215], s[52:53], 0, v[134:135]
	s_addc_u32 s47, s53, 0
	s_add_i32 s45, s45, s37
	global_load_lds_dwordx4 v[214:215], off
	v_lshl_add_u64 v[216:217], s[46:47], 0, v[32:33]
	s_mov_b32 m0, s45
	v_lshl_add_u64 v[218:219], s[56:57], 0, v[132:133]
	global_load_lds_dwordx4 v[216:217], off
	v_lshl_add_u64 v[216:217], s[46:47], 0, v[134:135]
	s_add_i32 m0, s45, 0x2000
	s_nop 0
	global_load_lds_dwordx4 v[216:217], off
	v_lshl_add_u64 v[216:217], s[56:57], 0, v[130:131]
	s_mov_b32 m0, s13
	s_nop 0
	global_load_lds_dwordx4 v[216:217], off
	s_mov_b32 m0, s24
	s_nop 0
	global_load_lds_dwordx4 v[218:219], off
	s_waitcnt vmcnt(24)
	s_waitcnt lgkmcnt(0)
	s_barrier
	s_setprio 1
	s_waitcnt lgkmcnt(0)
	v_mfma_f32_16x16x32_bf16 v[62:65], v[144:147], v[176:179], 0
	v_mfma_f32_16x16x32_bf16 v[58:61], v[152:155], v[176:179], 0
	v_mfma_f32_16x16x32_bf16 v[54:57], v[144:147], v[184:187], 0
	v_mfma_f32_16x16x32_bf16 v[50:53], v[152:155], v[184:187], 0
	v_mfma_f32_16x16x32_bf16 v[38:41], v[144:147], v[198:201], 0
	v_mfma_f32_16x16x32_bf16 v[34:37], v[152:155], v[198:201], 0
	v_mfma_f32_16x16x32_bf16 v[20:23], v[144:147], v[206:209], 0
	v_mfma_f32_16x16x32_bf16 v[16:19], v[152:155], v[206:209], 0
	v_mfma_f32_16x16x32_bf16 v[62:65], v[148:151], v[180:183], v[62:65]
	v_mfma_f32_16x16x32_bf16 v[58:61], v[156:159], v[180:183], v[58:61]
	v_mfma_f32_16x16x32_bf16 v[54:57], v[148:151], v[188:191], v[54:57]
	v_mfma_f32_16x16x32_bf16 v[50:53], v[156:159], v[188:191], v[50:53]
	v_mfma_f32_16x16x32_bf16 v[38:41], v[148:151], v[202:205], v[38:41]
	v_mfma_f32_16x16x32_bf16 v[34:37], v[156:159], v[202:205], v[34:37]
	v_mfma_f32_16x16x32_bf16 v[20:23], v[148:151], v[210:213], v[20:23]
	v_mfma_f32_16x16x32_bf16 v[16:19], v[156:159], v[210:213], v[16:19]
	s_setprio 0
	s_setprio 1
	v_mfma_f32_16x16x32_bf16 v[46:49], v[160:163], v[176:179], 0
	v_mfma_f32_16x16x32_bf16 v[42:45], v[168:171], v[176:179], 0
	v_mfma_f32_16x16x32_bf16 v[28:31], v[160:163], v[184:187], 0
	v_mfma_f32_16x16x32_bf16 v[24:27], v[168:171], v[184:187], 0
	v_mfma_f32_16x16x32_bf16 v[12:15], v[160:163], v[198:201], 0
	v_mfma_f32_16x16x32_bf16 v[8:11], v[168:171], v[198:201], 0
	v_mfma_f32_16x16x32_bf16 v[4:7], v[160:163], v[206:209], 0
	v_mfma_f32_16x16x32_bf16 v[0:3], v[168:171], v[206:209], 0
	v_mfma_f32_16x16x32_bf16 v[46:49], v[164:167], v[180:183], v[46:49]
	v_mfma_f32_16x16x32_bf16 v[42:45], v[172:175], v[180:183], v[42:45]
	v_mfma_f32_16x16x32_bf16 v[28:31], v[164:167], v[188:191], v[28:31]
	v_mfma_f32_16x16x32_bf16 v[24:27], v[172:175], v[188:191], v[24:27]
	v_mfma_f32_16x16x32_bf16 v[12:15], v[164:167], v[202:205], v[12:15]
	v_mfma_f32_16x16x32_bf16 v[8:11], v[172:175], v[202:205], v[8:11]
	v_mfma_f32_16x16x32_bf16 v[4:7], v[164:167], v[210:213], v[4:7]
	v_mfma_f32_16x16x32_bf16 v[0:3], v[172:175], v[210:213], v[0:3]
	s_setprio 0
	s_barrier
	s_add_i32 s45, 0, 0x18000
	s_add_i32 s50, 0, 0x1c000
	v_add_u32_e32 v156, s45, v141
	v_add_u32_e32 v172, s50, v141
	ds_read_b128 v[144:147], v156
	ds_read_b128 v[148:151], v156 offset:1024
	ds_read_b128 v[152:155], v156 offset:2048
	ds_read_b128 v[156:159], v156 offset:3072
	ds_read_b128 v[160:163], v172
	ds_read_b128 v[164:167], v172 offset:1024
	ds_read_b128 v[168:171], v172 offset:2048
	ds_read_b128 v[172:175], v172 offset:3072
	s_add_u32 s46, s56, 0x80000
	s_addc_u32 s47, s57, 0
	s_mov_b32 m0, s25
	v_lshl_add_u64 v[220:221], s[46:47], 0, v[130:131]
	ds_read_b128 v[176:179], v143 offset:32768
	ds_read_b128 v[180:183], v143 offset:33792
	ds_read_b128 v[184:187], v143 offset:34816
	ds_read_b128 v[188:191], v143 offset:35840
	ds_read_b128 v[198:201], v143 offset:36864
	ds_read_b128 v[202:205], v143 offset:37888
	ds_read_b128 v[206:209], v143 offset:38912
	ds_read_b128 v[210:213], v143 offset:39936
	global_load_lds_dwordx4 v[220:221], off
	v_lshl_add_u64 v[220:221], s[46:47], 0, v[132:133]
	s_mov_b32 m0, s38
	s_nop 0
	global_load_lds_dwordx4 v[220:221], off
	s_waitcnt vmcnt(16)
	s_waitcnt lgkmcnt(0)
	s_barrier
; #define PG8_STAGE(bufoff, gbase, voff) do { _Pragma("unroll") for (int _i = 0; _i < 2; ++_i) \
;         __builtin_amdgcn_global_load_lds((const unsigned*)((const char*)(gbase) + (voff)[_i]), (PG8_LAS unsigned*)(lds + (bufoff) + ldsw + _i * 8192), 16, 0, 0); } while (0)
; #define PG8_LDA(dst, b, h) do { _Pragma("unroll") for (int m = 0; m < 4; ++m) _Pragma("unroll") for (int k = 0; k < 2; ++k) dst[m][k] = *(const PG8_LAS bf16x8*)(lds + PG8_SA(b, h) + aoff + m * 2048 + k * 1024); } while (0)
; #define PG8_MMA(ai, bj, At, Bt) do { __builtin_amdgcn_s_setprio(1); _Pragma("unroll") for (int m = 0; m < 4; ++m) _Pragma("unroll") for (int n = 0; n < 2; ++n) _Pragma("unroll") for (int k = 0; k < 2; ++k) \
;         acc[ai][bj][m][n] = __builtin_amdgcn_mfma_f32_16x16x32_bf16(Bt[n][k], At[m][k], acc[ai][bj][m][n], 0, 0, 0); __builtin_amdgcn_s_setprio(0); } while (0)
; #define PG8_WAIT_V(n) asm volatile("s_waitcnt vmcnt(" #n ")" ::: "memory")
; #define PG8_WAIT_L(n) asm volatile("s_waitcnt lgkmcnt(" #n ")" ::: "memory")
; #define PG8_BAR __builtin_amdgcn_s_barrier()
; #define PG8_SCHED __builtin_amdgcn_sched_barrier(0)
; template <class Epi, class Sched, bool ALIGN_EPI = false, bool SP2 = false, bool KHOOK = false>
; __device__ __forceinline__ void gemm_phase(PG8_LAS unsigned char* lds, const Gemm g, const Sched& S, const Epi& E, const int tid_in) {
;     ...
;             PG8_WAIT_V(8); PG8_WAIT_L(0); PG8_BAR; PG8_MMA(0, 0, At, B0); PG8_MMA(0, 1, At, B1); PG8_BAR; PG8_SCHED;
;             PG8_LDA(At, 1, 1); PG8_STAGE(PG8_SB(1, 0), b3, voffB); PG8_STAGE(PG8_SB(1, 1), b3 + hstep, voffB); PG8_STAGE(PG8_SA(1, 0), a3, voffA);
;             PG8_WAIT_V(8); PG8_WAIT_L(0); PG8_BAR; PG8_MMA(1, 0, At, B0); PG8_MMA(1, 1, At, B1); PG8_BAR; PG8_SCHED;
	s_setprio 1
	s_waitcnt lgkmcnt(0)
	v_mfma_f32_16x16x32_bf16 v[126:129], v[144:147], v[176:179], v[126:129]
	v_mfma_f32_16x16x32_bf16 v[122:125], v[152:155], v[176:179], v[122:125]
	v_mfma_f32_16x16x32_bf16 v[118:121], v[144:147], v[184:187], v[118:121]
	v_mfma_f32_16x16x32_bf16 v[114:117], v[152:155], v[184:187], v[114:117]
	v_mfma_f32_16x16x32_bf16 v[102:105], v[144:147], v[198:201], v[102:105]
	v_mfma_f32_16x16x32_bf16 v[98:101], v[152:155], v[198:201], v[98:101]
	v_mfma_f32_16x16x32_bf16 v[86:89], v[144:147], v[206:209], v[86:89]
	v_mfma_f32_16x16x32_bf16 v[82:85], v[152:155], v[206:209], v[82:85]
	v_mfma_f32_16x16x32_bf16 v[126:129], v[148:151], v[180:183], v[126:129]
	v_mfma_f32_16x16x32_bf16 v[122:125], v[156:159], v[180:183], v[122:125]
	v_mfma_f32_16x16x32_bf16 v[118:121], v[148:151], v[188:191], v[118:121]
	v_mfma_f32_16x16x32_bf16 v[114:117], v[156:159], v[188:191], v[114:117]
	v_mfma_f32_16x16x32_bf16 v[102:105], v[148:151], v[202:205], v[102:105]
	v_mfma_f32_16x16x32_bf16 v[98:101], v[156:159], v[202:205], v[98:101]
	v_mfma_f32_16x16x32_bf16 v[86:89], v[148:151], v[210:213], v[86:89]
	v_mfma_f32_16x16x32_bf16 v[82:85], v[156:159], v[210:213], v[82:85]
	s_setprio 0
	s_setprio 1
	v_mfma_f32_16x16x32_bf16 v[110:113], v[160:163], v[176:179], v[110:113]
	v_mfma_f32_16x16x32_bf16 v[106:109], v[168:171], v[176:179], v[106:109]
	v_mfma_f32_16x16x32_bf16 v[94:97], v[160:163], v[184:187], v[94:97]
	v_mfma_f32_16x16x32_bf16 v[90:93], v[168:171], v[184:187], v[90:93]
	v_mfma_f32_16x16x32_bf16 v[78:81], v[160:163], v[198:201], v[78:81]
	v_mfma_f32_16x16x32_bf16 v[74:77], v[168:171], v[198:201], v[74:77]
	v_mfma_f32_16x16x32_bf16 v[70:73], v[160:163], v[206:209], v[70:73]
	v_mfma_f32_16x16x32_bf16 v[66:69], v[168:171], v[206:209], v[66:69]
	v_mfma_f32_16x16x32_bf16 v[110:113], v[164:167], v[180:183], v[110:113]
	v_mfma_f32_16x16x32_bf16 v[106:109], v[172:175], v[180:183], v[106:109]
	v_mfma_f32_16x16x32_bf16 v[94:97], v[164:167], v[188:191], v[94:97]
	v_mfma_f32_16x16x32_bf16 v[90:93], v[172:175], v[188:191], v[90:93]
	v_mfma_f32_16x16x32_bf16 v[78:81], v[164:167], v[202:205], v[78:81]
	v_mfma_f32_16x16x32_bf16 v[74:77], v[172:175], v[202:205], v[74:77]
	v_mfma_f32_16x16x32_bf16 v[70:73], v[164:167], v[210:213], v[70:73]
	v_mfma_f32_16x16x32_bf16 v[66:69], v[172:175], v[210:213], v[66:69]
	s_setprio 0
	s_barrier
	s_add_i32 s45, s45, s37
	v_lshl_add_u64 v[192:193], v[192:193], 0, s[90:91]
	s_mov_b32 m0, s45
	ds_read_b128 v[176:179], v143 offset:49152
	ds_read_b128 v[180:183], v143 offset:50176
	ds_read_b128 v[184:187], v143 offset:51200
	ds_read_b128 v[188:191], v143 offset:52224
	ds_read_b128 v[198:201], v143 offset:53248
	ds_read_b128 v[202:205], v143 offset:54272
	ds_read_b128 v[206:209], v143 offset:55296
	ds_read_b128 v[210:213], v143 offset:56320
	global_load_lds_dwordx4 v[192:193], off
	s_add_i32 m0, s45, 0x2000
	s_add_u32 s46, s52, 0x80080
	v_lshl_add_u64 v[192:193], v[214:215], 0, s[90:91]
	s_addc_u32 s47, s53, 0
	s_add_i32 s45, s50, s37
	global_load_lds_dwordx4 v[192:193], off
	v_lshl_add_u64 v[192:193], s[46:47], 0, v[32:33]
	s_mov_b32 m0, s45
	s_nop 0
	global_load_lds_dwordx4 v[192:193], off
	v_lshl_add_u64 v[192:193], s[46:47], 0, v[134:135]
	s_add_i32 m0, s45, 0x2000
	s_nop 0
	global_load_lds_dwordx4 v[192:193], off
	v_lshl_add_u64 v[192:193], v[216:217], 0, s[90:91]
	s_mov_b32 m0, s39
	s_nop 0
	global_load_lds_dwordx4 v[192:193], off
	v_lshl_add_u64 v[192:193], v[218:219], 0, s[90:91]
	s_mov_b32 m0, s40
	s_nop 0
	global_load_lds_dwordx4 v[192:193], off
	s_waitcnt vmcnt(8)
	s_waitcnt lgkmcnt(0)
	s_barrier
	s_setprio 1
	s_waitcnt lgkmcnt(0)
	v_mfma_f32_16x16x32_bf16 v[62:65], v[144:147], v[176:179], v[62:65]
	v_mfma_f32_16x16x32_bf16 v[58:61], v[152:155], v[176:179], v[58:61]
	v_mfma_f32_16x16x32_bf16 v[54:57], v[144:147], v[184:187], v[54:57]
	v_mfma_f32_16x16x32_bf16 v[50:53], v[152:155], v[184:187], v[50:53]
	v_mfma_f32_16x16x32_bf16 v[38:41], v[144:147], v[198:201], v[38:41]
	v_mfma_f32_16x16x32_bf16 v[34:37], v[152:155], v[198:201], v[34:37]
	v_mfma_f32_16x16x32_bf16 v[20:23], v[144:147], v[206:209], v[20:23]
	v_mfma_f32_16x16x32_bf16 v[16:19], v[152:155], v[206:209], v[16:19]
	v_mfma_f32_16x16x32_bf16 v[62:65], v[148:151], v[180:183], v[62:65]
	v_mfma_f32_16x16x32_bf16 v[58:61], v[156:159], v[180:183], v[58:61]
	v_mfma_f32_16x16x32_bf16 v[54:57], v[148:151], v[188:191], v[54:57]
	v_mfma_f32_16x16x32_bf16 v[50:53], v[156:159], v[188:191], v[50:53]
	v_mfma_f32_16x16x32_bf16 v[38:41], v[148:151], v[202:205], v[38:41]
	v_mfma_f32_16x16x32_bf16 v[34:37], v[156:159], v[202:205], v[34:37]
	v_mfma_f32_16x16x32_bf16 v[20:23], v[148:151], v[210:213], v[20:23]
	v_mfma_f32_16x16x32_bf16 v[16:19], v[156:159], v[210:213], v[16:19]
	s_setprio 0
	s_setprio 1
	v_mfma_f32_16x16x32_bf16 v[46:49], v[160:163], v[176:179], v[46:49]
	v_mfma_f32_16x16x32_bf16 v[42:45], v[168:171], v[176:179], v[42:45]
	v_mfma_f32_16x16x32_bf16 v[28:31], v[160:163], v[184:187], v[28:31]
	v_mfma_f32_16x16x32_bf16 v[24:27], v[168:171], v[184:187], v[24:27]
	v_mfma_f32_16x16x32_bf16 v[12:15], v[160:163], v[198:201], v[12:15]
	v_mfma_f32_16x16x32_bf16 v[8:11], v[168:171], v[198:201], v[8:11]
	v_mfma_f32_16x16x32_bf16 v[4:7], v[160:163], v[206:209], v[4:7]
	v_mfma_f32_16x16x32_bf16 v[0:3], v[168:171], v[206:209], v[0:3]
	v_mfma_f32_16x16x32_bf16 v[46:49], v[164:167], v[180:183], v[46:49]
	v_mfma_f32_16x16x32_bf16 v[42:45], v[172:175], v[180:183], v[42:45]
	v_mfma_f32_16x16x32_bf16 v[28:31], v[164:167], v[188:191], v[28:31]
	v_mfma_f32_16x16x32_bf16 v[24:27], v[172:175], v[188:191], v[24:27]
	v_mfma_f32_16x16x32_bf16 v[12:15], v[164:167], v[202:205], v[12:15]
	v_mfma_f32_16x16x32_bf16 v[8:11], v[172:175], v[202:205], v[8:11]
	v_mfma_f32_16x16x32_bf16 v[4:7], v[164:167], v[210:213], v[4:7]
	v_mfma_f32_16x16x32_bf16 v[0:3], v[172:175], v[210:213], v[0:3]
	s_setprio 0
	s_barrier
	s_add_i32 s44, s44, 2
	s_add_u32 s48, s48, 0x100
	s_addc_u32 s49, s49, 0
	s_add_u32 s19, s19, 0x100
	s_addc_u32 s42, s42, 0
	s_cmp_gt_u32 s44, 29
; #define PG8_STAGE(bufoff, gbase, voff) do { _Pragma("unroll") for (int _i = 0; _i < 2; ++_i) \
;         __builtin_amdgcn_global_load_lds((const unsigned*)((const char*)(gbase) + (voff)[_i]), (PG8_LAS unsigned*)(lds + (bufoff) + ldsw + _i * 8192), 16, 0, 0); } while (0)
; #define PG8_LDA(dst, b, h) do { _Pragma("unroll") for (int m = 0; m < 4; ++m) _Pragma("unroll") for (int k = 0; k < 2; ++k) dst[m][k] = *(const PG8_LAS bf16x8*)(lds + PG8_SA(b, h) + aoff + m * 2048 + k * 1024); } while (0)
; #define PG8_LDB(dst, b, h) do { _Pragma("unroll") for (int n = 0; n < 2; ++n) _Pragma("unroll") for (int k = 0; k < 2; ++k) dst[n][k] = *(const PG8_LAS bf16x8*)(lds + PG8_SB(b, h) + boff + n * 2048 + k * 1024); } while (0)
; #define PG8_MMA(ai, bj, At, Bt) do { __builtin_amdgcn_s_setprio(1); _Pragma("unroll") for (int m = 0; m < 4; ++m) _Pragma("unroll") for (int n = 0; n < 2; ++n) _Pragma("unroll") for (int k = 0; k < 2; ++k) \
;         acc[ai][bj][m][n] = __builtin_amdgcn_mfma_f32_16x16x32_bf16(Bt[n][k], At[m][k], acc[ai][bj][m][n], 0, 0, 0); __builtin_amdgcn_s_setprio(0); } while (0)
; #define PG8_WAIT_V(n) asm volatile("s_waitcnt vmcnt(" #n ")" ::: "memory")
; #define PG8_WAIT_L(n) asm volatile("s_waitcnt lgkmcnt(" #n ")" ::: "memory")
; #define PG8_BAR __builtin_amdgcn_s_barrier()
; template <class Epi, class Sched, bool ALIGN_EPI = false, bool SP2 = false, bool KHOOK = false>
; __device__ __forceinline__ void gemm_phase(PG8_LAS unsigned char* lds, const Gemm g, const Sched& S, const Epi& E, const int tid_in) {
;     ...
;         for (int t = 0; t < nt; t += 2) {
;             const bool last = (t == nt - 2);
;             const char* a1 = cA + (size_t)(t + 1) * kstep;
;             const char* a2 = last ? nA : cA + (size_t)(t + 2) * kstep; const char* b2 = last ? nB : cB + (size_t)(t + 2) * kstep;
;             const char* a3 = a2 + kstep; const char* b3 = b2 + kstep;
;             if (last && has_next) S.a_ready(nxt);
;             if constexpr (SP2) {
;             PG8_LDB(B0, 0, 0); PG8_LDB(B1, 0, 1); PG8_SCHED; PG8_LDA(At, 0, 0); PG8_STAGE(PG8_SA(1, 1), a1 + hstep, voffA);
;             PG8_WAIT_V(8); PG8_WAIT_L(0); PG8_BAR; PG8_MMA(0, 0, At, B0); PG8_MMA(0, 1, At, B1); PG8_BAR; PG8_SCHED;
;             PG8_LDA(At, 0, 1); PG8_STAGE(PG8_SB(0, 0), b2, voffB); PG8_STAGE(PG8_SB(0, 1), b2 + hstep, voffB); PG8_STAGE(PG8_SA(0, 0), a2, voffA);
.LBB0_263:
	s_add_u32 s45, s48, 0xfff80080
	s_addc_u32 s46, s49, -1
	s_add_i32 s47, 0, 0x10000
	s_cmp_eq_u32 s44, 28
	s_cselect_b32 s57, s11, s46
	s_cselect_b32 s56, s17, s45
	s_cselect_b32 s53, s15, s42
	s_cselect_b32 s52, s18, s19
	s_add_i32 s45, 0, 0x14000
	v_add_u32_e32 v156, s47, v141
	v_add_u32_e32 v172, s45, v141
	ds_read_b128 v[144:147], v156
	ds_read_b128 v[148:151], v156 offset:1024
	ds_read_b128 v[152:155], v156 offset:2048
	ds_read_b128 v[156:159], v156 offset:3072
	ds_read_b128 v[160:163], v172
	ds_read_b128 v[164:167], v172 offset:1024
	ds_read_b128 v[168:171], v172 offset:2048
	ds_read_b128 v[172:175], v172 offset:3072
	v_lshl_add_u64 v[192:193], s[48:49], 0, v[136:137]
	s_add_i32 m0, s13, 0xc000
	ds_read_b128 v[176:179], v143
	ds_read_b128 v[180:183], v143 offset:1024
	ds_read_b128 v[184:187], v143 offset:2048
	ds_read_b128 v[188:191], v143 offset:3072
	ds_read_b128 v[198:201], v143 offset:4096
	ds_read_b128 v[202:205], v143 offset:5120
	ds_read_b128 v[206:209], v143 offset:6144
	ds_read_b128 v[210:213], v143 offset:7168
	global_load_lds_dwordx4 v[192:193], off
	v_lshl_add_u64 v[192:193], s[48:49], 0, v[138:139]
	s_add_i32 m0, s13, 0xe000
	s_nop 0
	global_load_lds_dwordx4 v[192:193], off
	s_waitcnt vmcnt(8)
	s_waitcnt lgkmcnt(0)
	s_barrier
	s_setprio 1
	s_waitcnt lgkmcnt(0)
	v_mfma_f32_16x16x32_bf16 v[126:129], v[144:147], v[176:179], v[126:129]
	v_mfma_f32_16x16x32_bf16 v[122:125], v[152:155], v[176:179], v[122:125]
	v_mfma_f32_16x16x32_bf16 v[118:121], v[144:147], v[184:187], v[118:121]
	v_mfma_f32_16x16x32_bf16 v[114:117], v[152:155], v[184:187], v[114:117]
	v_mfma_f32_16x16x32_bf16 v[102:105], v[144:147], v[198:201], v[102:105]
	v_mfma_f32_16x16x32_bf16 v[98:101], v[152:155], v[198:201], v[98:101]
	v_mfma_f32_16x16x32_bf16 v[86:89], v[144:147], v[206:209], v[86:89]
	v_mfma_f32_16x16x32_bf16 v[82:85], v[152:155], v[206:209], v[82:85]
	v_mfma_f32_16x16x32_bf16 v[126:129], v[148:151], v[180:183], v[126:129]
	v_mfma_f32_16x16x32_bf16 v[122:125], v[156:159], v[180:183], v[122:125]
	v_mfma_f32_16x16x32_bf16 v[118:121], v[148:151], v[188:191], v[118:121]
	v_mfma_f32_16x16x32_bf16 v[114:117], v[156:159], v[188:191], v[114:117]
	v_mfma_f32_16x16x32_bf16 v[102:105], v[148:151], v[202:205], v[102:105]
	v_mfma_f32_16x16x32_bf16 v[98:101], v[156:159], v[202:205], v[98:101]
	v_mfma_f32_16x16x32_bf16 v[86:89], v[148:151], v[210:213], v[86:89]
	v_mfma_f32_16x16x32_bf16 v[82:85], v[156:159], v[210:213], v[82:85]
	s_setprio 0
	s_setprio 1
	v_mfma_f32_16x16x32_bf16 v[110:113], v[160:163], v[176:179], v[110:113]
	v_mfma_f32_16x16x32_bf16 v[106:109], v[168:171], v[176:179], v[106:109]
	v_mfma_f32_16x16x32_bf16 v[94:97], v[160:163], v[184:187], v[94:97]
	v_mfma_f32_16x16x32_bf16 v[90:93], v[168:171], v[184:187], v[90:93]
	v_mfma_f32_16x16x32_bf16 v[78:81], v[160:163], v[198:201], v[78:81]
	v_mfma_f32_16x16x32_bf16 v[74:77], v[168:171], v[198:201], v[74:77]
	v_mfma_f32_16x16x32_bf16 v[70:73], v[160:163], v[206:209], v[70:73]
	v_mfma_f32_16x16x32_bf16 v[66:69], v[168:171], v[206:209], v[66:69]
	v_mfma_f32_16x16x32_bf16 v[110:113], v[164:167], v[180:183], v[110:113]
	v_mfma_f32_16x16x32_bf16 v[106:109], v[172:175], v[180:183], v[106:109]
	v_mfma_f32_16x16x32_bf16 v[94:97], v[164:167], v[188:191], v[94:97]
	v_mfma_f32_16x16x32_bf16 v[90:93], v[172:175], v[188:191], v[90:93]
	v_mfma_f32_16x16x32_bf16 v[78:81], v[164:167], v[202:205], v[78:81]
	v_mfma_f32_16x16x32_bf16 v[74:77], v[172:175], v[202:205], v[74:77]
	v_mfma_f32_16x16x32_bf16 v[70:73], v[164:167], v[210:213], v[70:73]
	v_mfma_f32_16x16x32_bf16 v[66:69], v[172:175], v[210:213], v[66:69]
	s_setprio 0
	s_barrier
	s_add_i32 s46, s47, s37
	v_lshl_add_u64 v[192:193], s[52:53], 0, v[32:33]
	s_mov_b32 m0, s46
	ds_read_b128 v[176:179], v143 offset:16384
	ds_read_b128 v[180:183], v143 offset:17408
	ds_read_b128 v[184:187], v143 offset:18432
	ds_read_b128 v[188:191], v143 offset:19456
	ds_read_b128 v[198:201], v143 offset:20480
	ds_read_b128 v[202:205], v143 offset:21504
	ds_read_b128 v[206:209], v143 offset:22528
	ds_read_b128 v[210:213], v143 offset:23552
	global_load_lds_dwordx4 v[192:193], off
	s_add_i32 m0, s46, 0x2000
	s_add_u32 s46, s52, 0x80000
	v_lshl_add_u64 v[214:215], s[52:53], 0, v[134:135]
	s_addc_u32 s47, s53, 0
	s_add_i32 s45, s45, s37
	global_load_lds_dwordx4 v[214:215], off
	v_lshl_add_u64 v[216:217], s[46:47], 0, v[32:33]
	s_mov_b32 m0, s45
	v_lshl_add_u64 v[218:219], s[56:57], 0, v[132:133]
	global_load_lds_dwordx4 v[216:217], off
	v_lshl_add_u64 v[216:217], s[46:47], 0, v[134:135]
	s_add_i32 m0, s45, 0x2000
	s_nop 0
	global_load_lds_dwordx4 v[216:217], off
	v_lshl_add_u64 v[216:217], s[56:57], 0, v[130:131]
	s_mov_b32 m0, s13
	s_nop 0
	global_load_lds_dwordx4 v[216:217], off
	s_mov_b32 m0, s24
	s_nop 0
	global_load_lds_dwordx4 v[218:219], off
	s_waitcnt vmcnt(8)
	s_waitcnt lgkmcnt(0)
	s_barrier
; #define PG8_STAGE(bufoff, gbase, voff) do { _Pragma("unroll") for (int _i = 0; _i < 2; ++_i) \
;         __builtin_amdgcn_global_load_lds((const unsigned*)((const char*)(gbase) + (voff)[_i]), (PG8_LAS unsigned*)(lds + (bufoff) + ldsw + _i * 8192), 16, 0, 0); } while (0)
; #define PG8_LDA(dst, b, h) do { _Pragma("unroll") for (int m = 0; m < 4; ++m) _Pragma("unroll") for (int k = 0; k < 2; ++k) dst[m][k] = *(const PG8_LAS bf16x8*)(lds + PG8_SA(b, h) + aoff + m * 2048 + k * 1024); } while (0)
; #define PG8_LDB(dst, b, h) do { _Pragma("unroll") for (int n = 0; n < 2; ++n) _Pragma("unroll") for (int k = 0; k < 2; ++k) dst[n][k] = *(const PG8_LAS bf16x8*)(lds + PG8_SB(b, h) + boff + n * 2048 + k * 1024); } while (0)
; #define PG8_MMA(ai, bj, At, Bt) do { __builtin_amdgcn_s_setprio(1); _Pragma("unroll") for (int m = 0; m < 4; ++m) _Pragma("unroll") for (int n = 0; n < 2; ++n) _Pragma("unroll") for (int k = 0; k < 2; ++k) \
;         acc[ai][bj][m][n] = __builtin_amdgcn_mfma_f32_16x16x32_bf16(Bt[n][k], At[m][k], acc[ai][bj][m][n], 0, 0, 0); __builtin_amdgcn_s_setprio(0); } while (0)
; #define PG8_WAIT_V(n) asm volatile("s_waitcnt vmcnt(" #n ")" ::: "memory")
; #define PG8_WAIT_L(n) asm volatile("s_waitcnt lgkmcnt(" #n ")" ::: "memory")
; #define PG8_BAR __builtin_amdgcn_s_barrier()
; #define PG8_SCHED __builtin_amdgcn_sched_barrier(0)
; template <class Epi, class Sched, bool ALIGN_EPI = false, bool SP2 = false, bool KHOOK = false>
; __device__ __forceinline__ void gemm_phase(PG8_LAS unsigned char* lds, const Gemm g, const Sched& S, const Epi& E, const int tid_in) {
;     ...
;             PG8_WAIT_V(8); PG8_WAIT_L(0); PG8_BAR; PG8_MMA(1, 0, At, B0); PG8_MMA(1, 1, At, B1); PG8_BAR; PG8_SCHED;
;             PG8_LDB(B0, 1, 0); PG8_LDB(B1, 1, 1); PG8_SCHED; PG8_LDA(At, 1, 0); PG8_STAGE(PG8_SA(0, 1), a2 + hstep, voffA);
;             PG8_WAIT_V(8); PG8_WAIT_L(0); PG8_BAR; PG8_MMA(0, 0, At, B0); PG8_MMA(0, 1, At, B1); PG8_BAR; PG8_SCHED;
	s_setprio 1
	s_waitcnt lgkmcnt(0)
	v_mfma_f32_16x16x32_bf16 v[62:65], v[144:147], v[176:179], v[62:65]
	v_mfma_f32_16x16x32_bf16 v[58:61], v[152:155], v[176:179], v[58:61]
	v_mfma_f32_16x16x32_bf16 v[54:57], v[144:147], v[184:187], v[54:57]
	v_mfma_f32_16x16x32_bf16 v[50:53], v[152:155], v[184:187], v[50:53]
	v_mfma_f32_16x16x32_bf16 v[38:41], v[144:147], v[198:201], v[38:41]
	v_mfma_f32_16x16x32_bf16 v[34:37], v[152:155], v[198:201], v[34:37]
	v_mfma_f32_16x16x32_bf16 v[20:23], v[144:147], v[206:209], v[20:23]
	v_mfma_f32_16x16x32_bf16 v[16:19], v[152:155], v[206:209], v[16:19]
	v_mfma_f32_16x16x32_bf16 v[62:65], v[148:151], v[180:183], v[62:65]
	v_mfma_f32_16x16x32_bf16 v[58:61], v[156:159], v[180:183], v[58:61]
	v_mfma_f32_16x16x32_bf16 v[54:57], v[148:151], v[188:191], v[54:57]
	v_mfma_f32_16x16x32_bf16 v[50:53], v[156:159], v[188:191], v[50:53]
	v_mfma_f32_16x16x32_bf16 v[38:41], v[148:151], v[202:205], v[38:41]
	v_mfma_f32_16x16x32_bf16 v[34:37], v[156:159], v[202:205], v[34:37]
	v_mfma_f32_16x16x32_bf16 v[20:23], v[148:151], v[210:213], v[20:23]
	v_mfma_f32_16x16x32_bf16 v[16:19], v[156:159], v[210:213], v[16:19]
	s_setprio 0
	s_setprio 1
	v_mfma_f32_16x16x32_bf16 v[46:49], v[160:163], v[176:179], v[46:49]
	v_mfma_f32_16x16x32_bf16 v[42:45], v[168:171], v[176:179], v[42:45]
	v_mfma_f32_16x16x32_bf16 v[28:31], v[160:163], v[184:187], v[28:31]
	v_mfma_f32_16x16x32_bf16 v[24:27], v[168:171], v[184:187], v[24:27]
	v_mfma_f32_16x16x32_bf16 v[12:15], v[160:163], v[198:201], v[12:15]
	v_mfma_f32_16x16x32_bf16 v[8:11], v[168:171], v[198:201], v[8:11]
	v_mfma_f32_16x16x32_bf16 v[4:7], v[160:163], v[206:209], v[4:7]
	v_mfma_f32_16x16x32_bf16 v[0:3], v[168:171], v[206:209], v[0:3]
	v_mfma_f32_16x16x32_bf16 v[46:49], v[164:167], v[180:183], v[46:49]
	v_mfma_f32_16x16x32_bf16 v[42:45], v[172:175], v[180:183], v[42:45]
	v_mfma_f32_16x16x32_bf16 v[28:31], v[164:167], v[188:191], v[28:31]
	v_mfma_f32_16x16x32_bf16 v[24:27], v[172:175], v[188:191], v[24:27]
	v_mfma_f32_16x16x32_bf16 v[12:15], v[164:167], v[202:205], v[12:15]
	v_mfma_f32_16x16x32_bf16 v[8:11], v[172:175], v[202:205], v[8:11]
	v_mfma_f32_16x16x32_bf16 v[4:7], v[164:167], v[210:213], v[4:7]
	v_mfma_f32_16x16x32_bf16 v[0:3], v[172:175], v[210:213], v[0:3]
	s_setprio 0
	s_barrier
	s_add_i32 s45, 0, 0x18000
	s_add_i32 s50, 0, 0x1c000
	v_add_u32_e32 v156, s45, v141
	v_add_u32_e32 v172, s50, v141
	ds_read_b128 v[144:147], v156
	ds_read_b128 v[148:151], v156 offset:1024
	ds_read_b128 v[152:155], v156 offset:2048
	ds_read_b128 v[156:159], v156 offset:3072
	ds_read_b128 v[160:163], v172
	ds_read_b128 v[164:167], v172 offset:1024
	ds_read_b128 v[168:171], v172 offset:2048
	ds_read_b128 v[172:175], v172 offset:3072
	s_add_u32 s46, s56, 0x80000
	s_addc_u32 s47, s57, 0
	s_mov_b32 m0, s25
	v_lshl_add_u64 v[220:221], s[46:47], 0, v[130:131]
	ds_read_b128 v[176:179], v143 offset:32768
	ds_read_b128 v[180:183], v143 offset:33792
	ds_read_b128 v[184:187], v143 offset:34816
	ds_read_b128 v[188:191], v143 offset:35840
	ds_read_b128 v[198:201], v143 offset:36864
	ds_read_b128 v[202:205], v143 offset:37888
	ds_read_b128 v[206:209], v143 offset:38912
	ds_read_b128 v[210:213], v143 offset:39936
	global_load_lds_dwordx4 v[220:221], off
	v_lshl_add_u64 v[220:221], s[46:47], 0, v[132:133]
	s_mov_b32 m0, s38
	s_nop 0
	global_load_lds_dwordx4 v[220:221], off
	s_waitcnt vmcnt(8)
	s_waitcnt lgkmcnt(0)
	s_barrier
	s_setprio 1
	s_waitcnt lgkmcnt(0)
	v_mfma_f32_16x16x32_bf16 v[126:129], v[144:147], v[176:179], v[126:129]
	v_mfma_f32_16x16x32_bf16 v[122:125], v[152:155], v[176:179], v[122:125]
	v_mfma_f32_16x16x32_bf16 v[118:121], v[144:147], v[184:187], v[118:121]
	v_mfma_f32_16x16x32_bf16 v[114:117], v[152:155], v[184:187], v[114:117]
	v_mfma_f32_16x16x32_bf16 v[102:105], v[144:147], v[198:201], v[102:105]
	v_mfma_f32_16x16x32_bf16 v[98:101], v[152:155], v[198:201], v[98:101]
	v_mfma_f32_16x16x32_bf16 v[86:89], v[144:147], v[206:209], v[86:89]
	v_mfma_f32_16x16x32_bf16 v[82:85], v[152:155], v[206:209], v[82:85]
	v_mfma_f32_16x16x32_bf16 v[126:129], v[148:151], v[180:183], v[126:129]
	v_mfma_f32_16x16x32_bf16 v[122:125], v[156:159], v[180:183], v[122:125]
	v_mfma_f32_16x16x32_bf16 v[118:121], v[148:151], v[188:191], v[118:121]
	v_mfma_f32_16x16x32_bf16 v[114:117], v[156:159], v[188:191], v[114:117]
	v_mfma_f32_16x16x32_bf16 v[102:105], v[148:151], v[202:205], v[102:105]
	v_mfma_f32_16x16x32_bf16 v[98:101], v[156:159], v[202:205], v[98:101]
	v_mfma_f32_16x16x32_bf16 v[86:89], v[148:151], v[210:213], v[86:89]
	v_mfma_f32_16x16x32_bf16 v[82:85], v[156:159], v[210:213], v[82:85]
	s_setprio 0
	s_setprio 1
	v_mfma_f32_16x16x32_bf16 v[110:113], v[160:163], v[176:179], v[110:113]
	v_mfma_f32_16x16x32_bf16 v[106:109], v[168:171], v[176:179], v[106:109]
	v_mfma_f32_16x16x32_bf16 v[94:97], v[160:163], v[184:187], v[94:97]
	v_mfma_f32_16x16x32_bf16 v[90:93], v[168:171], v[184:187], v[90:93]
	v_mfma_f32_16x16x32_bf16 v[78:81], v[160:163], v[198:201], v[78:81]
	v_mfma_f32_16x16x32_bf16 v[74:77], v[168:171], v[198:201], v[74:77]
	v_mfma_f32_16x16x32_bf16 v[70:73], v[160:163], v[206:209], v[70:73]
	v_mfma_f32_16x16x32_bf16 v[66:69], v[168:171], v[206:209], v[66:69]
	v_mfma_f32_16x16x32_bf16 v[110:113], v[164:167], v[180:183], v[110:113]
	v_mfma_f32_16x16x32_bf16 v[106:109], v[172:175], v[180:183], v[106:109]
	v_mfma_f32_16x16x32_bf16 v[94:97], v[164:167], v[188:191], v[94:97]
	v_mfma_f32_16x16x32_bf16 v[90:93], v[172:175], v[188:191], v[90:93]
	v_mfma_f32_16x16x32_bf16 v[78:81], v[164:167], v[202:205], v[78:81]
	v_mfma_f32_16x16x32_bf16 v[74:77], v[172:175], v[202:205], v[74:77]
	v_mfma_f32_16x16x32_bf16 v[70:73], v[164:167], v[210:213], v[70:73]
	v_mfma_f32_16x16x32_bf16 v[66:69], v[172:175], v[210:213], v[66:69]
	s_setprio 0
	s_barrier
; #define PG8_STAGE(bufoff, gbase, voff) do { _Pragma("unroll") for (int _i = 0; _i < 2; ++_i) \
;         __builtin_amdgcn_global_load_lds((const unsigned*)((const char*)(gbase) + (voff)[_i]), (PG8_LAS unsigned*)(lds + (bufoff) + ldsw + _i * 8192), 16, 0, 0); } while (0)
; #define PG8_LDA(dst, b, h) do { _Pragma("unroll") for (int m = 0; m < 4; ++m) _Pragma("unroll") for (int k = 0; k < 2; ++k) dst[m][k] = *(const PG8_LAS bf16x8*)(lds + PG8_SA(b, h) + aoff + m * 2048 + k * 1024); } while (0)
; #define PG8_LDB(dst, b, h) do { _Pragma("unroll") for (int n = 0; n < 2; ++n) _Pragma("unroll") for (int k = 0; k < 2; ++k) dst[n][k] = *(const PG8_LAS bf16x8*)(lds + PG8_SB(b, h) + boff + n * 2048 + k * 1024); } while (0)
; #define PG8_MMA(ai, bj, At, Bt) do { __builtin_amdgcn_s_setprio(1); _Pragma("unroll") for (int m = 0; m < 4; ++m) _Pragma("unroll") for (int n = 0; n < 2; ++n) _Pragma("unroll") for (int k = 0; k < 2; ++k) \
;         acc[ai][bj][m][n] = __builtin_amdgcn_mfma_f32_16x16x32_bf16(Bt[n][k], At[m][k], acc[ai][bj][m][n], 0, 0, 0); __builtin_amdgcn_s_setprio(0); } while (0)
; #define PG8_WAIT_V(n) asm volatile("s_waitcnt vmcnt(" #n ")" ::: "memory")
; #define PG8_WAIT_L(n) asm volatile("s_waitcnt lgkmcnt(" #n ")" ::: "memory")
; #define PG8_BAR __builtin_amdgcn_s_barrier()
; template <class Epi, class Sched, bool ALIGN_EPI = false, bool SP2 = false, bool KHOOK = false>
; __device__ __forceinline__ void gemm_phase(PG8_LAS unsigned char* lds, const Gemm g, const Sched& S, const Epi& E, const int tid_in) {
;     ...
;         for (int t = 0; t < nt; t += 2) {
;             const bool last = (t == nt - 2);
;             const char* a1 = cA + (size_t)(t + 1) * kstep;
;             const char* a2 = last ? nA : cA + (size_t)(t + 2) * kstep; const char* b2 = last ? nB : cB + (size_t)(t + 2) * kstep;
;             const char* a3 = a2 + kstep; const char* b3 = b2 + kstep;
;             if (last && has_next) S.a_ready(nxt);
;             if constexpr (SP2) {
;             PG8_LDB(B0, 0, 0); PG8_LDB(B1, 0, 1); PG8_SCHED; PG8_LDA(At, 0, 0); PG8_STAGE(PG8_SA(1, 1), a1 + hstep, voffA);
;     ...
;             PG8_LDA(At, 1, 1); PG8_STAGE(PG8_SB(1, 0), b3, voffB); PG8_STAGE(PG8_SB(1, 1), b3 + hstep, voffB); PG8_STAGE(PG8_SA(1, 0), a3, voffA);
;             PG8_WAIT_V(8); PG8_WAIT_L(0); PG8_BAR; PG8_MMA(1, 0, At, B0); PG8_MMA(1, 1, At, B1); PG8_BAR; PG8_SCHED;
	s_add_i32 s45, s45, s37
	v_lshl_add_u64 v[192:193], v[192:193], 0, s[90:91]
	s_mov_b32 m0, s45
	ds_read_b128 v[176:179], v143 offset:49152
	ds_read_b128 v[180:183], v143 offset:50176
	ds_read_b128 v[184:187], v143 offset:51200
	ds_read_b128 v[188:191], v143 offset:52224
	ds_read_b128 v[198:201], v143 offset:53248
	ds_read_b128 v[202:205], v143 offset:54272
	ds_read_b128 v[206:209], v143 offset:55296
	ds_read_b128 v[210:213], v143 offset:56320
	global_load_lds_dwordx4 v[192:193], off
	s_add_i32 m0, s45, 0x2000
	s_add_u32 s46, s52, 0x80080
	v_lshl_add_u64 v[192:193], v[214:215], 0, s[90:91]
	s_addc_u32 s47, s53, 0
	s_add_i32 s45, s50, s37
	global_load_lds_dwordx4 v[192:193], off
	v_lshl_add_u64 v[192:193], s[46:47], 0, v[32:33]
	s_mov_b32 m0, s45
	s_nop 0
	global_load_lds_dwordx4 v[192:193], off
	v_lshl_add_u64 v[192:193], s[46:47], 0, v[134:135]
	s_add_i32 m0, s45, 0x2000
	s_nop 0
	global_load_lds_dwordx4 v[192:193], off
	v_lshl_add_u64 v[192:193], v[216:217], 0, s[90:91]
	s_mov_b32 m0, s39
	s_nop 0
	global_load_lds_dwordx4 v[192:193], off
	v_lshl_add_u64 v[192:193], v[218:219], 0, s[90:91]
	s_mov_b32 m0, s40
	s_nop 0
	global_load_lds_dwordx4 v[192:193], off
	s_waitcnt vmcnt(8)
	s_waitcnt lgkmcnt(0)
	s_barrier
	s_setprio 1
	s_waitcnt lgkmcnt(0)
	v_mfma_f32_16x16x32_bf16 v[62:65], v[144:147], v[176:179], v[62:65]
	v_mfma_f32_16x16x32_bf16 v[58:61], v[152:155], v[176:179], v[58:61]
	v_mfma_f32_16x16x32_bf16 v[54:57], v[144:147], v[184:187], v[54:57]
	v_mfma_f32_16x16x32_bf16 v[50:53], v[152:155], v[184:187], v[50:53]
	v_mfma_f32_16x16x32_bf16 v[38:41], v[144:147], v[198:201], v[38:41]
	v_mfma_f32_16x16x32_bf16 v[34:37], v[152:155], v[198:201], v[34:37]
	v_mfma_f32_16x16x32_bf16 v[20:23], v[144:147], v[206:209], v[20:23]
	v_mfma_f32_16x16x32_bf16 v[16:19], v[152:155], v[206:209], v[16:19]
	v_mfma_f32_16x16x32_bf16 v[62:65], v[148:151], v[180:183], v[62:65]
	v_mfma_f32_16x16x32_bf16 v[58:61], v[156:159], v[180:183], v[58:61]
	v_mfma_f32_16x16x32_bf16 v[54:57], v[148:151], v[188:191], v[54:57]
	v_mfma_f32_16x16x32_bf16 v[50:53], v[156:159], v[188:191], v[50:53]
	v_mfma_f32_16x16x32_bf16 v[38:41], v[148:151], v[202:205], v[38:41]
	v_mfma_f32_16x16x32_bf16 v[34:37], v[156:159], v[202:205], v[34:37]
	v_mfma_f32_16x16x32_bf16 v[20:23], v[148:151], v[210:213], v[20:23]
	v_mfma_f32_16x16x32_bf16 v[16:19], v[156:159], v[210:213], v[16:19]
	s_setprio 0
	s_setprio 1
	v_mfma_f32_16x16x32_bf16 v[46:49], v[160:163], v[176:179], v[46:49]
	v_mfma_f32_16x16x32_bf16 v[42:45], v[168:171], v[176:179], v[42:45]
	v_mfma_f32_16x16x32_bf16 v[28:31], v[160:163], v[184:187], v[28:31]
	v_mfma_f32_16x16x32_bf16 v[24:27], v[168:171], v[184:187], v[24:27]
	v_mfma_f32_16x16x32_bf16 v[12:15], v[160:163], v[198:201], v[12:15]
	v_mfma_f32_16x16x32_bf16 v[8:11], v[168:171], v[198:201], v[8:11]
	v_mfma_f32_16x16x32_bf16 v[4:7], v[160:163], v[206:209], v[4:7]
	v_mfma_f32_16x16x32_bf16 v[0:3], v[168:171], v[206:209], v[0:3]
	v_mfma_f32_16x16x32_bf16 v[46:49], v[164:167], v[180:183], v[46:49]
	v_mfma_f32_16x16x32_bf16 v[42:45], v[172:175], v[180:183], v[42:45]
	v_mfma_f32_16x16x32_bf16 v[28:31], v[164:167], v[188:191], v[28:31]
	v_mfma_f32_16x16x32_bf16 v[24:27], v[172:175], v[188:191], v[24:27]
	v_mfma_f32_16x16x32_bf16 v[12:15], v[164:167], v[202:205], v[12:15]
	v_mfma_f32_16x16x32_bf16 v[8:11], v[172:175], v[202:205], v[8:11]
	v_mfma_f32_16x16x32_bf16 v[4:7], v[164:167], v[210:213], v[4:7]
	v_mfma_f32_16x16x32_bf16 v[0:3], v[172:175], v[210:213], v[0:3]
	s_setprio 0
	s_barrier
	s_add_i32 s44, s44, 2
	s_add_u32 s48, s48, 0x100
	s_addc_u32 s49, s49, 0
	s_add_u32 s19, s19, 0x100
	s_addc_u32 s42, s42, 0
	s_cmp_lg_u32 s44, 28
	s_cbranch_scc1 .Lg1_cont
	s_cmp_lg_u64 s[22:23], 0
	s_cbranch_scc1 .Lg1_last
.Lg1_cont:
	s_cmp_gt_u32 s44, 29
	s_cbranch_scc0 .LBB0_263
	s_branch .Lg1_kexit
.Lg1_last:
	s_add_u32 s45, s48, 0xfff80080
	s_addc_u32 s46, s49, -1
	s_add_i32 s47, 0, 0x10000
	s_cmp_eq_u32 s44, 28
	s_cselect_b32 s57, s11, s46
	s_cselect_b32 s56, s17, s45
	s_cselect_b32 s53, s15, s42
	s_cselect_b32 s52, s18, s19
	s_add_i32 s45, 0, 0x14000
	v_add_u32_e32 v156, s47, v141
	v_add_u32_e32 v172, s45, v141
	ds_read_b128 v[144:147], v156
	ds_read_b128 v[148:151], v156 offset:1024
	ds_read_b128 v[152:155], v156 offset:2048
	ds_read_b128 v[156:159], v156 offset:3072
	ds_read_b128 v[160:163], v172
	ds_read_b128 v[164:167], v172 offset:1024
	ds_read_b128 v[168:171], v172 offset:2048
	ds_read_b128 v[172:175], v172 offset:3072
	v_lshl_add_u64 v[192:193], s[48:49], 0, v[136:137]
	s_add_i32 m0, s13, 0xc000
	ds_read_b128 v[176:179], v143
	ds_read_b128 v[180:183], v143 offset:1024
	ds_read_b128 v[184:187], v143 offset:2048
	ds_read_b128 v[188:191], v143 offset:3072
	ds_read_b128 v[198:201], v143 offset:4096
	ds_read_b128 v[202:205], v143 offset:5120
	ds_read_b128 v[206:209], v143 offset:6144
	ds_read_b128 v[210:213], v143 offset:7168
	global_load_lds_dwordx4 v[192:193], off
	v_lshl_add_u64 v[192:193], s[48:49], 0, v[138:139]
	s_add_i32 m0, s13, 0xe000
	s_nop 0
	global_load_lds_dwordx4 v[192:193], off
	s_waitcnt vmcnt(8)
	s_waitcnt lgkmcnt(0)
	s_barrier
; #define PG8_STAGE(bufoff, gbase, voff) do { _Pragma("unroll") for (int _i = 0; _i < 2; ++_i) \
;         __builtin_amdgcn_global_load_lds((const unsigned*)((const char*)(gbase) + (voff)[_i]), (PG8_LAS unsigned*)(lds + (bufoff) + ldsw + _i * 8192), 16, 0, 0); } while (0)
; #define PG8_LDA(dst, b, h) do { _Pragma("unroll") for (int m = 0; m < 4; ++m) _Pragma("unroll") for (int k = 0; k < 2; ++k) dst[m][k] = *(const PG8_LAS bf16x8*)(lds + PG8_SA(b, h) + aoff + m * 2048 + k * 1024); } while (0)
; #define PG8_LDB(dst, b, h) do { _Pragma("unroll") for (int n = 0; n < 2; ++n) _Pragma("unroll") for (int k = 0; k < 2; ++k) dst[n][k] = *(const PG8_LAS bf16x8*)(lds + PG8_SB(b, h) + boff + n * 2048 + k * 1024); } while (0)
; #define PG8_MMA(ai, bj, At, Bt) do { __builtin_amdgcn_s_setprio(1); _Pragma("unroll") for (int m = 0; m < 4; ++m) _Pragma("unroll") for (int n = 0; n < 2; ++n) _Pragma("unroll") for (int k = 0; k < 2; ++k) \
;         acc[ai][bj][m][n] = __builtin_amdgcn_mfma_f32_16x16x32_bf16(Bt[n][k], At[m][k], acc[ai][bj][m][n], 0, 0, 0); __builtin_amdgcn_s_setprio(0); } while (0)
; #define PG8_WAIT_V(n) asm volatile("s_waitcnt vmcnt(" #n ")" ::: "memory")
; #define PG8_WAIT_L(n) asm volatile("s_waitcnt lgkmcnt(" #n ")" ::: "memory")
; #define PG8_BAR __builtin_amdgcn_s_barrier()
; #define PG8_SCHED __builtin_amdgcn_sched_barrier(0)
; template <class Epi, class Sched, bool ALIGN_EPI = false, bool SP2 = false, bool KHOOK = false>
; __device__ __forceinline__ void gemm_phase(PG8_LAS unsigned char* lds, const Gemm g, const Sched& S, const Epi& E, const int tid_in) {
;     ...
;             PG8_LDB(B0, 0, 0); PG8_LDB(B1, 0, 1); PG8_SCHED; PG8_LDA(At, 0, 0); PG8_STAGE(PG8_SA(1, 1), a1 + hstep, voffA);
;             PG8_WAIT_V(8); PG8_WAIT_L(0); PG8_BAR; PG8_MMA(0, 0, At, B0); PG8_MMA(0, 1, At, B1); PG8_BAR; PG8_SCHED;
;             PG8_LDA(At, 0, 1); PG8_STAGE(PG8_SB(0, 0), b2, voffB); PG8_STAGE(PG8_SB(0, 1), b2 + hstep, voffB); PG8_STAGE(PG8_SA(0, 0), a2, voffA);
;             PG8_WAIT_V(8); PG8_WAIT_L(0); PG8_BAR; PG8_MMA(1, 0, At, B0); PG8_MMA(1, 1, At, B1); PG8_BAR; PG8_SCHED;
	s_setprio 1
	s_waitcnt lgkmcnt(0)
	v_mfma_f32_16x16x32_bf16 v[126:129], v[144:147], v[176:179], v[126:129]
	v_mfma_f32_16x16x32_bf16 v[122:125], v[152:155], v[176:179], v[122:125]
	v_mfma_f32_16x16x32_bf16 v[118:121], v[144:147], v[184:187], v[118:121]
	v_mfma_f32_16x16x32_bf16 v[114:117], v[152:155], v[184:187], v[114:117]
	v_mfma_f32_16x16x32_bf16 v[102:105], v[144:147], v[198:201], v[102:105]
	v_mfma_f32_16x16x32_bf16 v[98:101], v[152:155], v[198:201], v[98:101]
	v_mfma_f32_16x16x32_bf16 v[86:89], v[144:147], v[206:209], v[86:89]
	v_mfma_f32_16x16x32_bf16 v[82:85], v[152:155], v[206:209], v[82:85]
	v_mfma_f32_16x16x32_bf16 v[126:129], v[148:151], v[180:183], v[126:129]
	v_mfma_f32_16x16x32_bf16 v[122:125], v[156:159], v[180:183], v[122:125]
	v_mfma_f32_16x16x32_bf16 v[118:121], v[148:151], v[188:191], v[118:121]
	v_mfma_f32_16x16x32_bf16 v[114:117], v[156:159], v[188:191], v[114:117]
	v_mfma_f32_16x16x32_bf16 v[102:105], v[148:151], v[202:205], v[102:105]
	v_mfma_f32_16x16x32_bf16 v[98:101], v[156:159], v[202:205], v[98:101]
	v_mfma_f32_16x16x32_bf16 v[86:89], v[148:151], v[210:213], v[86:89]
	v_mfma_f32_16x16x32_bf16 v[82:85], v[156:159], v[210:213], v[82:85]
	s_setprio 0
	s_setprio 1
	v_mfma_f32_16x16x32_bf16 v[110:113], v[160:163], v[176:179], v[110:113]
	v_mfma_f32_16x16x32_bf16 v[106:109], v[168:171], v[176:179], v[106:109]
	v_mfma_f32_16x16x32_bf16 v[94:97], v[160:163], v[184:187], v[94:97]
	v_mfma_f32_16x16x32_bf16 v[90:93], v[168:171], v[184:187], v[90:93]
	v_mfma_f32_16x16x32_bf16 v[78:81], v[160:163], v[198:201], v[78:81]
	v_mfma_f32_16x16x32_bf16 v[74:77], v[168:171], v[198:201], v[74:77]
	v_mfma_f32_16x16x32_bf16 v[70:73], v[160:163], v[206:209], v[70:73]
	v_mfma_f32_16x16x32_bf16 v[66:69], v[168:171], v[206:209], v[66:69]
	v_mfma_f32_16x16x32_bf16 v[110:113], v[164:167], v[180:183], v[110:113]
	v_mfma_f32_16x16x32_bf16 v[106:109], v[172:175], v[180:183], v[106:109]
	v_mfma_f32_16x16x32_bf16 v[94:97], v[164:167], v[188:191], v[94:97]
	v_mfma_f32_16x16x32_bf16 v[90:93], v[172:175], v[188:191], v[90:93]
	v_mfma_f32_16x16x32_bf16 v[78:81], v[164:167], v[202:205], v[78:81]
	v_mfma_f32_16x16x32_bf16 v[74:77], v[172:175], v[202:205], v[74:77]
	v_mfma_f32_16x16x32_bf16 v[70:73], v[164:167], v[210:213], v[70:73]
	v_mfma_f32_16x16x32_bf16 v[66:69], v[172:175], v[210:213], v[66:69]
	s_setprio 0
	s_barrier
	s_add_i32 s46, s47, s37
	v_lshl_add_u64 v[192:193], s[52:53], 0, v[32:33]
	s_mov_b32 m0, s46
	ds_read_b128 v[176:179], v143 offset:16384
	ds_read_b128 v[180:183], v143 offset:17408
	ds_read_b128 v[184:187], v143 offset:18432
	ds_read_b128 v[188:191], v143 offset:19456
	ds_read_b128 v[198:201], v143 offset:20480
	ds_read_b128 v[202:205], v143 offset:21504
	ds_read_b128 v[206:209], v143 offset:22528
	ds_read_b128 v[210:213], v143 offset:23552
	global_load_lds_dwordx4 v[192:193], off
	s_add_i32 m0, s46, 0x2000
	s_add_u32 s46, s52, 0x80000
	v_lshl_add_u64 v[214:215], s[52:53], 0, v[134:135]
	s_addc_u32 s47, s53, 0
	s_add_i32 s45, s45, s37
	global_load_lds_dwordx4 v[214:215], off
	v_lshl_add_u64 v[216:217], s[46:47], 0, v[32:33]
	s_mov_b32 m0, s45
	v_lshl_add_u64 v[218:219], s[56:57], 0, v[132:133]
	global_load_lds_dwordx4 v[216:217], off
	v_lshl_add_u64 v[216:217], s[46:47], 0, v[134:135]
	s_add_i32 m0, s45, 0x2000
	s_nop 0
	global_load_lds_dwordx4 v[216:217], off
	v_lshl_add_u64 v[216:217], s[56:57], 0, v[130:131]
	s_mov_b32 m0, s13
	s_nop 0
	global_load_lds_dwordx4 v[216:217], off
	s_mov_b32 m0, s24
	s_nop 0
	global_load_lds_dwordx4 v[218:219], off
	s_waitcnt vmcnt(8)
	s_waitcnt lgkmcnt(0)
	s_barrier
	s_setprio 1
	s_waitcnt lgkmcnt(0)
	v_mfma_f32_16x16x32_bf16 v[62:65], v[144:147], v[176:179], v[62:65]
	v_mfma_f32_16x16x32_bf16 v[58:61], v[152:155], v[176:179], v[58:61]
	v_mfma_f32_16x16x32_bf16 v[54:57], v[144:147], v[184:187], v[54:57]
	v_mfma_f32_16x16x32_bf16 v[50:53], v[152:155], v[184:187], v[50:53]
	v_mfma_f32_16x16x32_bf16 v[38:41], v[144:147], v[198:201], v[38:41]
	v_mfma_f32_16x16x32_bf16 v[34:37], v[152:155], v[198:201], v[34:37]
	v_mfma_f32_16x16x32_bf16 v[20:23], v[144:147], v[206:209], v[20:23]
	v_mfma_f32_16x16x32_bf16 v[16:19], v[152:155], v[206:209], v[16:19]
	v_mfma_f32_16x16x32_bf16 v[62:65], v[148:151], v[180:183], v[62:65]
	v_mfma_f32_16x16x32_bf16 v[58:61], v[156:159], v[180:183], v[58:61]
	v_mfma_f32_16x16x32_bf16 v[54:57], v[148:151], v[188:191], v[54:57]
	v_mfma_f32_16x16x32_bf16 v[50:53], v[156:159], v[188:191], v[50:53]
	v_mfma_f32_16x16x32_bf16 v[38:41], v[148:151], v[202:205], v[38:41]
	v_mfma_f32_16x16x32_bf16 v[34:37], v[156:159], v[202:205], v[34:37]
	v_mfma_f32_16x16x32_bf16 v[20:23], v[148:151], v[210:213], v[20:23]
	v_mfma_f32_16x16x32_bf16 v[16:19], v[156:159], v[210:213], v[16:19]
	s_setprio 0
	s_setprio 1
	v_mfma_f32_16x16x32_bf16 v[46:49], v[160:163], v[176:179], v[46:49]
	v_mfma_f32_16x16x32_bf16 v[42:45], v[168:171], v[176:179], v[42:45]
	v_mfma_f32_16x16x32_bf16 v[28:31], v[160:163], v[184:187], v[28:31]
	v_mfma_f32_16x16x32_bf16 v[24:27], v[168:171], v[184:187], v[24:27]
	v_mfma_f32_16x16x32_bf16 v[12:15], v[160:163], v[198:201], v[12:15]
	v_mfma_f32_16x16x32_bf16 v[8:11], v[168:171], v[198:201], v[8:11]
	v_mfma_f32_16x16x32_bf16 v[4:7], v[160:163], v[206:209], v[4:7]
	v_mfma_f32_16x16x32_bf16 v[0:3], v[168:171], v[206:209], v[0:3]
	v_mfma_f32_16x16x32_bf16 v[46:49], v[164:167], v[180:183], v[46:49]
	v_mfma_f32_16x16x32_bf16 v[42:45], v[172:175], v[180:183], v[42:45]
	v_mfma_f32_16x16x32_bf16 v[28:31], v[164:167], v[188:191], v[28:31]
	v_mfma_f32_16x16x32_bf16 v[24:27], v[172:175], v[188:191], v[24:27]
	v_mfma_f32_16x16x32_bf16 v[12:15], v[164:167], v[202:205], v[12:15]
	v_mfma_f32_16x16x32_bf16 v[8:11], v[172:175], v[202:205], v[8:11]
	v_mfma_f32_16x16x32_bf16 v[4:7], v[164:167], v[210:213], v[4:7]
	v_mfma_f32_16x16x32_bf16 v[0:3], v[172:175], v[210:213], v[0:3]
	s_setprio 0
	s_barrier
; #define PG8_STAGE(bufoff, gbase, voff) do { _Pragma("unroll") for (int _i = 0; _i < 2; ++_i) \
;         __builtin_amdgcn_global_load_lds((const unsigned*)((const char*)(gbase) + (voff)[_i]), (PG8_LAS unsigned*)(lds + (bufoff) + ldsw + _i * 8192), 16, 0, 0); } while (0)
; #define PG8_LDA(dst, b, h) do { _Pragma("unroll") for (int m = 0; m < 4; ++m) _Pragma("unroll") for (int k = 0; k < 2; ++k) dst[m][k] = *(const PG8_LAS bf16x8*)(lds + PG8_SA(b, h) + aoff + m * 2048 + k * 1024); } while (0)
; #define PG8_LDB(dst, b, h) do { _Pragma("unroll") for (int n = 0; n < 2; ++n) _Pragma("unroll") for (int k = 0; k < 2; ++k) dst[n][k] = *(const PG8_LAS bf16x8*)(lds + PG8_SB(b, h) + boff + n * 2048 + k * 1024); } while (0)
; #define PG8_MMA(ai, bj, At, Bt) do { __builtin_amdgcn_s_setprio(1); _Pragma("unroll") for (int m = 0; m < 4; ++m) _Pragma("unroll") for (int n = 0; n < 2; ++n) _Pragma("unroll") for (int k = 0; k < 2; ++k) \
;         acc[ai][bj][m][n] = __builtin_amdgcn_mfma_f32_16x16x32_bf16(Bt[n][k], At[m][k], acc[ai][bj][m][n], 0, 0, 0); __builtin_amdgcn_s_setprio(0); } while (0)
; #define PG8_WAIT_V(n) asm volatile("s_waitcnt vmcnt(" #n ")" ::: "memory")
; #define PG8_WAIT_L(n) asm volatile("s_waitcnt lgkmcnt(" #n ")" ::: "memory")
; #define PG8_BAR __builtin_amdgcn_s_barrier()
; #define PG8_SCHED __builtin_amdgcn_sched_barrier(0)
; template <class Epi, class Sched, bool ALIGN_EPI = false, bool SP2 = false, bool KHOOK = false>
; __device__ __forceinline__ void gemm_phase(PG8_LAS unsigned char* lds, const Gemm g, const Sched& S, const Epi& E, const int tid_in) {
;     ...
;             PG8_LDB(B0, 1, 0); PG8_LDB(B1, 1, 1); PG8_SCHED; PG8_LDA(At, 1, 0); PG8_STAGE(PG8_SA(0, 1), a2 + hstep, voffA);
;             PG8_WAIT_V(8); PG8_WAIT_L(0); PG8_BAR; PG8_MMA(0, 0, At, B0); PG8_MMA(0, 1, At, B1); PG8_BAR; PG8_SCHED;
	s_add_i32 s45, 0, 0x18000
	s_add_i32 s50, 0, 0x1c000
	v_add_u32_e32 v156, s45, v141
	v_add_u32_e32 v172, s50, v141
	ds_read_b128 v[144:147], v156
	ds_read_b128 v[148:151], v156 offset:1024
	ds_read_b128 v[152:155], v156 offset:2048
	ds_read_b128 v[156:159], v156 offset:3072
	ds_read_b128 v[160:163], v172
	ds_read_b128 v[164:167], v172 offset:1024
	ds_read_b128 v[168:171], v172 offset:2048
	ds_read_b128 v[172:175], v172 offset:3072
	s_add_u32 s46, s56, 0x80000
	s_addc_u32 s47, s57, 0
	s_mov_b32 m0, s25
	v_lshl_add_u64 v[220:221], s[46:47], 0, v[130:131]
	ds_read_b128 v[176:179], v143 offset:32768
	ds_read_b128 v[180:183], v143 offset:33792
	ds_read_b128 v[184:187], v143 offset:34816
	ds_read_b128 v[188:191], v143 offset:35840
	ds_read_b128 v[198:201], v143 offset:36864
	ds_read_b128 v[202:205], v143 offset:37888
	ds_read_b128 v[206:209], v143 offset:38912
	ds_read_b128 v[210:213], v143 offset:39936
	global_load_lds_dwordx4 v[220:221], off
	v_lshl_add_u64 v[220:221], s[46:47], 0, v[132:133]
	s_mov_b32 m0, s38
	s_nop 0
	global_load_lds_dwordx4 v[220:221], off
	s_waitcnt vmcnt(8)
	s_waitcnt lgkmcnt(0)
	s_barrier
	s_setprio 1
	s_waitcnt lgkmcnt(0)
	v_mfma_f32_16x16x32_bf16 v[126:129], v[144:147], v[176:179], v[126:129]
	v_mfma_f32_16x16x32_bf16 v[122:125], v[152:155], v[176:179], v[122:125]
	v_mfma_f32_16x16x32_bf16 v[118:121], v[144:147], v[184:187], v[118:121]
	v_mfma_f32_16x16x32_bf16 v[114:117], v[152:155], v[184:187], v[114:117]
	v_mfma_f32_16x16x32_bf16 v[102:105], v[144:147], v[198:201], v[102:105]
	v_mfma_f32_16x16x32_bf16 v[98:101], v[152:155], v[198:201], v[98:101]
	v_mfma_f32_16x16x32_bf16 v[86:89], v[144:147], v[206:209], v[86:89]
	v_mfma_f32_16x16x32_bf16 v[82:85], v[152:155], v[206:209], v[82:85]
	v_mfma_f32_16x16x32_bf16 v[126:129], v[148:151], v[180:183], v[126:129]
	v_mfma_f32_16x16x32_bf16 v[122:125], v[156:159], v[180:183], v[122:125]
	v_mfma_f32_16x16x32_bf16 v[118:121], v[148:151], v[188:191], v[118:121]
	v_mfma_f32_16x16x32_bf16 v[114:117], v[156:159], v[188:191], v[114:117]
	v_mfma_f32_16x16x32_bf16 v[102:105], v[148:151], v[202:205], v[102:105]
	v_mfma_f32_16x16x32_bf16 v[98:101], v[156:159], v[202:205], v[98:101]
	v_mfma_f32_16x16x32_bf16 v[86:89], v[148:151], v[210:213], v[86:89]
	v_mfma_f32_16x16x32_bf16 v[82:85], v[156:159], v[210:213], v[82:85]
	s_setprio 0
	s_setprio 1
	v_mfma_f32_16x16x32_bf16 v[110:113], v[160:163], v[176:179], v[110:113]
	v_mfma_f32_16x16x32_bf16 v[106:109], v[168:171], v[176:179], v[106:109]
	v_mfma_f32_16x16x32_bf16 v[94:97], v[160:163], v[184:187], v[94:97]
	v_mfma_f32_16x16x32_bf16 v[90:93], v[168:171], v[184:187], v[90:93]
	v_mfma_f32_16x16x32_bf16 v[78:81], v[160:163], v[198:201], v[78:81]
	v_mfma_f32_16x16x32_bf16 v[74:77], v[168:171], v[198:201], v[74:77]
	v_mfma_f32_16x16x32_bf16 v[70:73], v[160:163], v[206:209], v[70:73]
	v_mfma_f32_16x16x32_bf16 v[66:69], v[168:171], v[206:209], v[66:69]
	v_mfma_f32_16x16x32_bf16 v[110:113], v[164:167], v[180:183], v[110:113]
	v_mfma_f32_16x16x32_bf16 v[106:109], v[172:175], v[180:183], v[106:109]
	v_mfma_f32_16x16x32_bf16 v[94:97], v[164:167], v[188:191], v[94:97]
	v_mfma_f32_16x16x32_bf16 v[90:93], v[172:175], v[188:191], v[90:93]
	v_mfma_f32_16x16x32_bf16 v[78:81], v[164:167], v[202:205], v[78:81]
	v_mfma_f32_16x16x32_bf16 v[74:77], v[172:175], v[202:205], v[74:77]
	v_mfma_f32_16x16x32_bf16 v[70:73], v[164:167], v[210:213], v[70:73]
	v_mfma_f32_16x16x32_bf16 v[66:69], v[172:175], v[210:213], v[66:69]
	s_setprio 0
	s_barrier
; __device__ __forceinline__ unsigned cvt_pk_bf16(float lo, float hi) { const f32x2_t v = {lo, hi}; const bf16x2_t c = __builtin_convertvector(v, bf16x2_t); return __builtin_bit_cast(unsigned, c); }
; #define PG8_STAGE(bufoff, gbase, voff) do { _Pragma("unroll") for (int _i = 0; _i < 2; ++_i) \
;         __builtin_amdgcn_global_load_lds((const unsigned*)((const char*)(gbase) + (voff)[_i]), (PG8_LAS unsigned*)(lds + (bufoff) + ldsw + _i * 8192), 16, 0, 0); } while (0)
; #define PG8_LDA(dst, b, h) do { _Pragma("unroll") for (int m = 0; m < 4; ++m) _Pragma("unroll") for (int k = 0; k < 2; ++k) dst[m][k] = *(const PG8_LAS bf16x8*)(lds + PG8_SA(b, h) + aoff + m * 2048 + k * 1024); } while (0)
; #define PG8_MMA(ai, bj, At, Bt) do { __builtin_amdgcn_s_setprio(1); _Pragma("unroll") for (int m = 0; m < 4; ++m) _Pragma("unroll") for (int n = 0; n < 2; ++n) _Pragma("unroll") for (int k = 0; k < 2; ++k) \
;         acc[ai][bj][m][n] = __builtin_amdgcn_mfma_f32_16x16x32_bf16(Bt[n][k], At[m][k], acc[ai][bj][m][n], 0, 0, 0); __builtin_amdgcn_s_setprio(0); } while (0)
; #define PG8_WAIT_V(n) asm volatile("s_waitcnt vmcnt(" #n ")" ::: "memory")
; #define PG8_WAIT_L(n) asm volatile("s_waitcnt lgkmcnt(" #n ")" ::: "memory")
;     __device__ __forceinline__ void operator()(const f32x4 (&acc)[2][2][4][2], const Unit& u, int wr, int wc, int fr, int fq) const {
;     ...
;         for (int ai = 0; ai < 2; ++ai)
; #pragma unroll
;             for (int m = 0; m < 4; ++m) { bf16_t* rowp = O + (size_t)(row0 + ai * HALF + m * 16) * ldc + col0;
; #pragma unroll
;                 for (int bj = 0; bj < 2; ++bj) { const f32x4 v0 = acc[ai][bj][m][0], v1 = acc[ai][bj][m][1];
;                     u32x4 w; w.x = cvt_pk_bf16(v0[0], v0[1]); w.y = cvt_pk_bf16(v0[2], v0[3]); w.z = cvt_pk_bf16(v1[0], v1[1]); w.w = cvt_pk_bf16(v1[2], v1[3]);
;                     *(u32x4*)(rowp + bj * HALF) = w; } }
; template <class Epi, class Sched, bool ALIGN_EPI = false, bool SP2 = false, bool KHOOK = false>
; __device__ __forceinline__ void gemm_phase(PG8_LAS unsigned char* lds, const Gemm g, const Sched& S, const Epi& E, const int tid_in) {
;     ...
;             PG8_LDA(At, 1, 1); PG8_STAGE(PG8_SB(1, 0), b3, voffB); PG8_STAGE(PG8_SB(1, 1), b3 + hstep, voffB); PG8_STAGE(PG8_SA(1, 0), a3, voffA);
;             PG8_WAIT_V(8); PG8_WAIT_L(0); PG8_BAR; PG8_MMA(1, 0, At, B0); PG8_MMA(1, 1, At, B1); PG8_BAR; PG8_SCHED;
	s_add_i32 s45, s45, s37
	v_lshl_add_u64 v[192:193], v[192:193], 0, s[90:91]
	s_mov_b32 m0, s45
	ds_read_b128 v[176:179], v143 offset:49152
	ds_read_b128 v[180:183], v143 offset:50176
	ds_read_b128 v[184:187], v143 offset:51200
	ds_read_b128 v[188:191], v143 offset:52224
	ds_read_b128 v[198:201], v143 offset:53248
	ds_read_b128 v[202:205], v143 offset:54272
	ds_read_b128 v[206:209], v143 offset:55296
	ds_read_b128 v[210:213], v143 offset:56320
	global_load_lds_dwordx4 v[192:193], off
	s_add_i32 m0, s45, 0x2000
	s_add_u32 s46, s52, 0x80080
	v_lshl_add_u64 v[192:193], v[214:215], 0, s[90:91]
	s_addc_u32 s47, s53, 0
	s_add_i32 s45, s50, s37
	global_load_lds_dwordx4 v[192:193], off
	v_lshl_add_u64 v[192:193], s[46:47], 0, v[32:33]
	s_mov_b32 m0, s45
	s_nop 0
	global_load_lds_dwordx4 v[192:193], off
	v_lshl_add_u64 v[192:193], s[46:47], 0, v[134:135]
	s_add_i32 m0, s45, 0x2000
	s_nop 0
	global_load_lds_dwordx4 v[192:193], off
	v_lshl_add_u64 v[192:193], v[216:217], 0, s[90:91]
	s_mov_b32 m0, s39
	s_nop 0
	global_load_lds_dwordx4 v[192:193], off
	v_lshl_add_u64 v[192:193], v[218:219], 0, s[90:91]
	s_mov_b32 m0, s40
	s_nop 0
	global_load_lds_dwordx4 v[192:193], off
	v_lshl_add_u32 v246, s12, 8, v140
	v_lshl_or_b32 v222, s10, 8, v142
	v_lshlrev_b32_e32 v222, 1, v222
	v_mov_b32_e32 v223, 0
	v_mad_u64_u32 v[248:249], s[70:71], v246, s67, v[222:223]
	s_mov_b32 s72, 0xa2000
	s_mov_b32 s73, 0
	v_lshl_add_u64 v[248:249], v[248:249], 0, s[76:77]
	v_cvt_pk_bf16_f32 v126, v126, v127
	v_cvt_pk_bf16_f32 v127, v128, v129
	v_cvt_pk_bf16_f32 v128, v122, v123
	v_cvt_pk_bf16_f32 v129, v124, v125
	global_store_dwordx4 v[248:249], v[126:129], off
	v_cvt_pk_bf16_f32 v110, v110, v111
	v_cvt_pk_bf16_f32 v111, v112, v113
	v_cvt_pk_bf16_f32 v112, v106, v107
	v_cvt_pk_bf16_f32 v113, v108, v109
	global_store_dwordx4 v[248:249], v[110:113], off offset:256
	v_lshl_add_u64 v[248:249], v[248:249], 0, s[72:73]
	v_cvt_pk_bf16_f32 v118, v118, v119
	v_cvt_pk_bf16_f32 v119, v120, v121
	v_cvt_pk_bf16_f32 v120, v114, v115
	v_cvt_pk_bf16_f32 v121, v116, v117
	global_store_dwordx4 v[248:249], v[118:121], off
	v_cvt_pk_bf16_f32 v94, v94, v95
	v_cvt_pk_bf16_f32 v95, v96, v97
	v_cvt_pk_bf16_f32 v96, v90, v91
	v_cvt_pk_bf16_f32 v97, v92, v93
	global_store_dwordx4 v[248:249], v[94:97], off offset:256
	v_lshl_add_u64 v[248:249], v[248:249], 0, s[72:73]
	v_cvt_pk_bf16_f32 v102, v102, v103
	v_cvt_pk_bf16_f32 v103, v104, v105
	v_cvt_pk_bf16_f32 v104, v98, v99
	v_cvt_pk_bf16_f32 v105, v100, v101
	global_store_dwordx4 v[248:249], v[102:105], off
	v_cvt_pk_bf16_f32 v78, v78, v79
	v_cvt_pk_bf16_f32 v79, v80, v81
	v_cvt_pk_bf16_f32 v80, v74, v75
	v_cvt_pk_bf16_f32 v81, v76, v77
	global_store_dwordx4 v[248:249], v[78:81], off offset:256
	v_lshl_add_u64 v[248:249], v[248:249], 0, s[72:73]
	v_cvt_pk_bf16_f32 v86, v86, v87
	v_cvt_pk_bf16_f32 v87, v88, v89
	v_cvt_pk_bf16_f32 v88, v82, v83
	v_cvt_pk_bf16_f32 v89, v84, v85
	global_store_dwordx4 v[248:249], v[86:89], off
	v_cvt_pk_bf16_f32 v70, v70, v71
	v_cvt_pk_bf16_f32 v71, v72, v73
	v_cvt_pk_bf16_f32 v72, v66, v67
	v_cvt_pk_bf16_f32 v73, v68, v69
	global_store_dwordx4 v[248:249], v[70:73], off offset:256
	s_waitcnt vmcnt(16)
	s_waitcnt lgkmcnt(0)
	s_barrier
	s_setprio 1
	s_waitcnt lgkmcnt(0)
	v_mfma_f32_16x16x32_bf16 v[62:65], v[144:147], v[176:179], v[62:65]
	v_mfma_f32_16x16x32_bf16 v[58:61], v[152:155], v[176:179], v[58:61]
	v_mfma_f32_16x16x32_bf16 v[54:57], v[144:147], v[184:187], v[54:57]
	v_mfma_f32_16x16x32_bf16 v[50:53], v[152:155], v[184:187], v[50:53]
	v_mfma_f32_16x16x32_bf16 v[38:41], v[144:147], v[198:201], v[38:41]
	v_mfma_f32_16x16x32_bf16 v[34:37], v[152:155], v[198:201], v[34:37]
	v_mfma_f32_16x16x32_bf16 v[20:23], v[144:147], v[206:209], v[20:23]
	v_mfma_f32_16x16x32_bf16 v[16:19], v[152:155], v[206:209], v[16:19]
	v_mfma_f32_16x16x32_bf16 v[62:65], v[148:151], v[180:183], v[62:65]
	v_mfma_f32_16x16x32_bf16 v[58:61], v[156:159], v[180:183], v[58:61]
	v_mfma_f32_16x16x32_bf16 v[54:57], v[148:151], v[188:191], v[54:57]
	v_mfma_f32_16x16x32_bf16 v[50:53], v[156:159], v[188:191], v[50:53]
	v_mfma_f32_16x16x32_bf16 v[38:41], v[148:151], v[202:205], v[38:41]
	v_mfma_f32_16x16x32_bf16 v[34:37], v[156:159], v[202:205], v[34:37]
	v_mfma_f32_16x16x32_bf16 v[20:23], v[148:151], v[210:213], v[20:23]
	v_mfma_f32_16x16x32_bf16 v[16:19], v[156:159], v[210:213], v[16:19]
	s_setprio 0
	s_setprio 1
	v_mfma_f32_16x16x32_bf16 v[46:49], v[160:163], v[176:179], v[46:49]
	v_mfma_f32_16x16x32_bf16 v[42:45], v[168:171], v[176:179], v[42:45]
	v_mfma_f32_16x16x32_bf16 v[28:31], v[160:163], v[184:187], v[28:31]
	v_mfma_f32_16x16x32_bf16 v[24:27], v[168:171], v[184:187], v[24:27]
	v_mfma_f32_16x16x32_bf16 v[12:15], v[160:163], v[198:201], v[12:15]
	v_mfma_f32_16x16x32_bf16 v[8:11], v[168:171], v[198:201], v[8:11]
	v_mfma_f32_16x16x32_bf16 v[4:7], v[160:163], v[206:209], v[4:7]
	v_mfma_f32_16x16x32_bf16 v[0:3], v[168:171], v[206:209], v[0:3]
	v_mfma_f32_16x16x32_bf16 v[46:49], v[164:167], v[180:183], v[46:49]
	v_mfma_f32_16x16x32_bf16 v[42:45], v[172:175], v[180:183], v[42:45]
	v_mfma_f32_16x16x32_bf16 v[28:31], v[164:167], v[188:191], v[28:31]
	v_mfma_f32_16x16x32_bf16 v[24:27], v[172:175], v[188:191], v[24:27]
	v_mfma_f32_16x16x32_bf16 v[12:15], v[164:167], v[202:205], v[12:15]
	v_mfma_f32_16x16x32_bf16 v[8:11], v[172:175], v[202:205], v[8:11]
	v_mfma_f32_16x16x32_bf16 v[4:7], v[164:167], v[210:213], v[4:7]
	v_mfma_f32_16x16x32_bf16 v[0:3], v[172:175], v[210:213], v[0:3]
	s_setprio 0
	s_barrier
	s_add_i32 s44, s44, 2
	s_add_u32 s48, s48, 0x100
	s_addc_u32 s49, s49, 0
	s_add_u32 s19, s19, 0x100
	s_addc_u32 s42, s42, 0
	s_mov_b32 s68, s12
	s_mov_b32 s69, s10
	s_mov_b32 s60, 1
	s_branch .LBB0_257
.Lg1_kexit:
	s_and_b64 vcc, exec, s[8:9]
	s_cbranch_vccz .LBB0_266
	s_barrier
